# v11: convert_weights loads batched in LN2 phase + hand-scheduled attention QK phase (scalar addressing, 20 K loads in flight)
# speedup vs baseline: 1.0394x; 1.0124x over previous
; __device__ __forceinline__ f32x4 mfma16(bf16x8 a, bf16x8 b, f32x4 c) { return __builtin_amdgcn_mfma_f32_16x16x32_bf16(a, b, c, 0, 0, 0); }
; __device__ __forceinline__ void attn_phase(const bf16* proj, bf16* mixed, const float* rpb, const float* gain_a, LAS unsigned char* lds, int vb, int nb, int wave, int lane_in) {
;     ...
;         const int row_start = min(max(r - 4, 0), R - 8), blk_start = min(max(16 * cb - 8, 0), 32);
;         const int qtok = base + 64 * r + 16 * cb + qi;
;         bf16x8 qf[4];
; #pragma unroll
;         for (int ks = 0; ks < 4; ++ks) qf[ks] = *(const bf16x8*)(proj + (size_t)qtok * NIN + C_AQ + h * 128 + ks * 32 + g * 8);
;         f32x4 sc[16];
; #pragma unroll
;         for (int tq = 0; tq < 2; ++tq) {
;             bf16x8 kf[8][4];
; #pragma unroll
;             for (int tt = 0; tt < 8; ++tt) { const int t = 8 * tq + tt;
;                 const int ktok = base + 64 * (row_start + (t >> 1)) + blk_start + 16 * (t & 1) + qi;
;                 const bf16* kp = proj + (size_t)ktok * NIN + C_AK + h * 128 + g * 8;
; #pragma unroll
;                 for (int ks = 0; ks < 4; ++ks) kf[tt][ks] = *(const bf16x8*)(kp + ks * 32); }
; #pragma unroll
;             for (int tt = 0; tt < 8; ++tt) { f32x4 a = {0.f, 0.f, 0.f, 0.f};
; #pragma unroll
;                 for (int ks = 0; ks < 4; ++ks) a = mfma16(kf[tt][ks], qf[ks], a);
;                 sc[8 * tq + tt] = a; }
.LBB0_431:
	s_and_b32 s4, s27, 48
	v_sub_u32_e64 v11, s4, 8 clamp
	v_and_b32_e32 v91, 15, v1
	v_sub_u32_e64 v10, s30, 4 clamp
	v_min_u32_e32 v72, 32, v11
	v_ashrrev_i32_e32 v71, 4, v1
	v_min_u32_e32 v73, s5, v10
	v_add_u32_e32 v10, v72, v91
	v_lshlrev_b32_e32 v4, 3, v71
	v_or_b32_e32 v99, s29, v10
	v_lshlrev_b32_e32 v128, 6, v73
	v_mov_b64_e32 v[6:7], s[50:51]
	v_ashrrev_i32_e32 v5, 31, v4
	v_add_u32_e32 v10, v128, v99
	s_lshl_b32 s31, s30, 6
	v_lshlrev_b64 v[8:9], 1, v[4:5]
	v_mad_i64_i32 v[10:11], s[54:55], v10, s33, v[6:7]
	v_add_u32_e32 v118, 64, v128
	s_add_i32 s31, s31, s29
	v_lshl_add_u64 v[60:61], v[10:11], 0, v[8:9]
	v_add_u32_e32 v14, v118, v99
	s_or_b32 s31, s31, s4
	v_mad_i64_i32 v[14:15], s[54:55], v14, s33, v[6:7]
	v_or_b32_e32 v70, s31, v91
	v_lshl_add_u64 v[66:67], v[14:15], 0, v[8:9]
	v_mad_i64_i32 v[2:3], s[54:55], v70, s33, v[6:7]
	v_add_u32_e32 v108, 16, v99
	v_lshl_add_u64 v[58:59], v[2:3], 0, v[8:9]
	v_add_u32_e32 v22, v108, v128
	v_mad_i64_i32 v[26:27], s[54:55], v22, s33, v[6:7]
	v_add_u32_e32 v109, 0x80, v128
	v_add_u32_e32 v18, v109, v99
	v_mad_i64_i32 v[18:19], s[54:55], v18, s33, v[6:7]
	v_lshl_add_u64 v[68:69], v[18:19], 0, v[8:9]
	v_lshl_add_u64 v[82:83], v[26:27], 0, v[8:9]
	v_add_u32_e32 v34, v118, v108
	v_mad_i64_i32 v[34:35], s[54:55], v34, s33, v[6:7]
	v_lshl_add_u64 v[88:89], v[34:35], 0, v[8:9]
	v_add_u32_e32 v46, v109, v108
	v_mad_i64_i32 v[46:47], s[54:55], v46, s33, v[6:7]
	v_lshl_add_u64 v[96:97], v[46:47], 0, v[8:9]
	v_add_u32_e32 v98, 0xc0, v128
	v_subrev_u32_e32 v73, s30, v73
	v_add_u32_e32 v46, v98, v99
	v_add_u32_e32 v88, 0x1c0, v128
	v_mad_i64_i32 v[14:15], s[54:55], v46, s33, v[6:7]
	v_lshl_add_u64 v[82:83], v[14:15], 0, v[8:9]
	v_add_u32_e32 v97, 0x100, v128
	v_add_u32_e32 v34, v98, v108
	v_add_u32_e32 v94, 0x140, v128
	v_add_u32_e32 v93, 0x180, v128
	v_lshlrev_b32_e32 v92, 2, v71
	v_mad_i64_i32 v[10:11], s[54:55], v34, s33, v[6:7]
	v_lshl_add_u64 v[26:27], v[10:11], 0, v[8:9]
	v_add_u32_e32 v10, v97, v99
	v_mad_i64_i32 v[10:11], s[54:55], v10, s33, v[6:7]
	v_lshl_add_u64 v[34:35], v[10:11], 0, v[8:9]
	v_add_u32_e32 v34, v97, v108
	v_mad_i64_i32 v[34:35], s[54:55], v34, s33, v[6:7]
	v_lshl_add_u64 v[82:83], v[34:35], 0, v[8:9]
	v_add_u32_e32 v82, v94, v99
	v_mad_i64_i32 v[30:31], s[54:55], v82, s33, v[6:7]
	v_lshl_add_u64 v[82:83], v[30:31], 0, v[8:9]
	v_add_u32_e32 v82, v94, v108
	v_mad_i64_i32 v[22:23], s[54:55], v82, s33, v[6:7]
	v_lshl_add_u64 v[82:83], v[22:23], 0, v[8:9]
	v_add_u32_e32 v82, v93, v99
	v_mad_i64_i32 v[22:23], s[54:55], v82, s33, v[6:7]
	v_lshl_add_u64 v[82:83], v[22:23], 0, v[8:9]
	v_add_u32_e32 v18, v93, v108
	v_mad_i64_i32 v[18:19], s[54:55], v18, s33, v[6:7]
	v_lshl_add_u64 v[82:83], v[18:19], 0, v[8:9]
	v_add_u32_e32 v82, v88, v99
	v_mad_i64_i32 v[14:15], s[54:55], v82, s33, v[6:7]
	v_lshl_add_u64 v[82:83], v[14:15], 0, v[8:9]
	v_add_u32_e32 v82, v88, v108
	v_mad_i64_i32 v[6:7], s[54:55], v82, s33, v[6:7]
	v_lshl_add_u64 v[82:83], v[6:7], 0, v[8:9]
	v_or_b32_e32 v79, s4, v91
	v_sub_u32_e64 v78, v79, 8 clamp
	v_min_u32_e32 v80, 48, v78
	v_add_u32_e32 v81, v72, v92
	v_add_u32_e32 v82, 16, v80
	v_mul_u32_u24_e32 v250, s33, v91
	v_lshl_add_u32 v250, v71, 4, v250
	s_mul_i32 s100, s31, s33
	s_add_u32 s100, s50, s100
	s_addc_u32 s101, s51, 0
	global_load_dwordx4 v[130:133], v250, s[100:101]
	global_load_dwordx4 v[134:137], v250, s[100:101] offset:64
	global_load_dwordx4 v[138:141], v250, s[100:101] offset:128
	global_load_dwordx4 v[142:145], v250, s[100:101] offset:192
	s_sub_i32 s100, s4, 8
	s_max_i32 s100, s100, 0
	s_min_i32 s100, s100, 32
	s_sub_i32 s101, s30, 4
	s_max_i32 s101, s101, 0
	s_min_i32 s101, s101, s5
	s_lshl_b32 s101, s101, 6
	s_add_i32 s100, s100, s101
	s_add_i32 s100, s100, s29
	s_mul_i32 s100, s100, s33
	s_add_u32 s100, s50, s100
	s_addc_u32 s101, s51, 0
	s_add_u32 s100, s100, 0x800
	s_addc_u32 s101, s101, 0
	global_load_dwordx4 v[148:151], v250, s[100:101]
	global_load_dwordx4 v[152:155], v250, s[100:101] offset:64
	global_load_dwordx4 v[156:159], v250, s[100:101] offset:128
	global_load_dwordx4 v[160:163], v250, s[100:101] offset:192
	s_add_u32 s100, s100, 0x70000
	s_addc_u32 s101, s101, 0
	global_load_dwordx4 v[164:167], v250, s[100:101]
	global_load_dwordx4 v[168:171], v250, s[100:101] offset:64
	global_load_dwordx4 v[172:175], v250, s[100:101] offset:128
	global_load_dwordx4 v[176:179], v250, s[100:101] offset:192
	s_add_u32 s100, s100, 0x150000
	s_addc_u32 s101, s101, 0
	global_load_dwordx4 v[198:201], v250, s[100:101]
	global_load_dwordx4 v[202:205], v250, s[100:101] offset:64
	global_load_dwordx4 v[206:209], v250, s[100:101] offset:128
	global_load_dwordx4 v[230:233], v250, s[100:101] offset:192
	s_add_u32 s100, s100, 0x70000
	s_addc_u32 s101, s101, 0
	global_load_dwordx4 v[234:237], v250, s[100:101]
	global_load_dwordx4 v[238:241], v250, s[100:101] offset:64
	global_load_dwordx4 v[242:245], v250, s[100:101] offset:128
	global_load_dwordx4 v[246:249], v250, s[100:101] offset:192
	s_add_u32 s100, s100, 0x150000
	s_addc_u32 s101, s101, 0
	global_load_dwordx4 v[100:103], v250, s[100:101]
	global_load_dwordx4 v[104:107], v250, s[100:101] offset:64
	global_load_dwordx4 v[110:113], v250, s[100:101] offset:128
	global_load_dwordx4 v[114:117], v250, s[100:101] offset:192
	s_add_u32 s100, s100, 0x70000
	s_addc_u32 s101, s101, 0
	s_waitcnt vmcnt(12)
; __device__ __forceinline__ f32x4 mfma16(bf16x8 a, bf16x8 b, f32x4 c) { return __builtin_amdgcn_mfma_f32_16x16x32_bf16(a, b, c, 0, 0, 0); }
; __device__ __forceinline__ void attn_phase(const bf16* proj, bf16* mixed, const float* rpb, const float* gain_a, LAS unsigned char* lds, int vb, int nb, int wave, int lane_in) {
;     ...
;         for (int tq = 0; tq < 2; ++tq) {
;             bf16x8 kf[8][4];
; #pragma unroll
;             for (int tt = 0; tt < 8; ++tt) { const int t = 8 * tq + tt;
;                 const int ktok = base + 64 * (row_start + (t >> 1)) + blk_start + 16 * (t & 1) + qi;
;                 const bf16* kp = proj + (size_t)ktok * NIN + C_AK + h * 128 + g * 8;
; #pragma unroll
;                 for (int ks = 0; ks < 4; ++ks) kf[tt][ks] = *(const bf16x8*)(kp + ks * 32); }
; #pragma unroll
;             for (int tt = 0; tt < 8; ++tt) { f32x4 a = {0.f, 0.f, 0.f, 0.f};
; #pragma unroll
;                 for (int ks = 0; ks < 4; ++ks) a = mfma16(kf[tt][ks], qf[ks], a);
;                 sc[8 * tq + tt] = a; }
	v_mfma_f32_16x16x32_bf16 v[66:69], v[148:151], v[130:133], 0
	v_mfma_f32_16x16x32_bf16 v[58:61], v[164:167], v[130:133], 0
	v_mfma_f32_16x16x32_bf16 v[66:69], v[152:155], v[134:137], v[66:69]
	v_mfma_f32_16x16x32_bf16 v[58:61], v[168:171], v[134:137], v[58:61]
	v_mfma_f32_16x16x32_bf16 v[66:69], v[156:159], v[138:141], v[66:69]
	v_mfma_f32_16x16x32_bf16 v[58:61], v[172:175], v[138:141], v[58:61]
	v_mfma_f32_16x16x32_bf16 v[66:69], v[160:163], v[142:145], v[66:69]
	v_mfma_f32_16x16x32_bf16 v[58:61], v[176:179], v[142:145], v[58:61]
	global_load_dwordx4 v[148:151], v250, s[100:101]
	global_load_dwordx4 v[152:155], v250, s[100:101] offset:64
	global_load_dwordx4 v[156:159], v250, s[100:101] offset:128
	global_load_dwordx4 v[160:163], v250, s[100:101] offset:192
	s_add_u32 s100, s100, 0x150000
	s_addc_u32 s101, s101, 0
	global_load_dwordx4 v[164:167], v250, s[100:101]
	global_load_dwordx4 v[168:171], v250, s[100:101] offset:64
	global_load_dwordx4 v[172:175], v250, s[100:101] offset:128
	global_load_dwordx4 v[176:179], v250, s[100:101] offset:192
	s_add_u32 s100, s100, 0x70000
	s_addc_u32 s101, s101, 0
	s_waitcnt vmcnt(12)
	v_mfma_f32_16x16x32_bf16 v[54:57], v[198:201], v[130:133], 0
	v_mfma_f32_16x16x32_bf16 v[50:53], v[234:237], v[130:133], 0
	v_mfma_f32_16x16x32_bf16 v[54:57], v[202:205], v[134:137], v[54:57]
	v_mfma_f32_16x16x32_bf16 v[50:53], v[238:241], v[134:137], v[50:53]
	v_mfma_f32_16x16x32_bf16 v[54:57], v[206:209], v[138:141], v[54:57]
	v_mfma_f32_16x16x32_bf16 v[50:53], v[242:245], v[138:141], v[50:53]
	v_mfma_f32_16x16x32_bf16 v[54:57], v[230:233], v[142:145], v[54:57]
	v_mfma_f32_16x16x32_bf16 v[50:53], v[246:249], v[142:145], v[50:53]
	global_load_dwordx4 v[198:201], v250, s[100:101]
	global_load_dwordx4 v[202:205], v250, s[100:101] offset:64
	global_load_dwordx4 v[206:209], v250, s[100:101] offset:128
	global_load_dwordx4 v[230:233], v250, s[100:101] offset:192
	s_add_u32 s100, s100, 0x150000
	s_addc_u32 s101, s101, 0
	global_load_dwordx4 v[234:237], v250, s[100:101]
	global_load_dwordx4 v[238:241], v250, s[100:101] offset:64
	global_load_dwordx4 v[242:245], v250, s[100:101] offset:128
	global_load_dwordx4 v[246:249], v250, s[100:101] offset:192
	s_add_u32 s100, s100, 0x70000
	s_addc_u32 s101, s101, 0
	s_waitcnt vmcnt(12)
	v_mfma_f32_16x16x32_bf16 v[46:49], v[100:103], v[130:133], 0
	v_mfma_f32_16x16x32_bf16 v[42:45], v[148:151], v[130:133], 0
	v_mfma_f32_16x16x32_bf16 v[46:49], v[104:107], v[134:137], v[46:49]
	v_mfma_f32_16x16x32_bf16 v[42:45], v[152:155], v[134:137], v[42:45]
	v_mfma_f32_16x16x32_bf16 v[46:49], v[110:113], v[138:141], v[46:49]
	v_mfma_f32_16x16x32_bf16 v[42:45], v[156:159], v[138:141], v[42:45]
	v_mfma_f32_16x16x32_bf16 v[46:49], v[114:117], v[142:145], v[46:49]
	v_mfma_f32_16x16x32_bf16 v[42:45], v[160:163], v[142:145], v[42:45]
	global_load_dwordx4 v[100:103], v250, s[100:101]
	global_load_dwordx4 v[104:107], v250, s[100:101] offset:64
	global_load_dwordx4 v[110:113], v250, s[100:101] offset:128
	global_load_dwordx4 v[114:117], v250, s[100:101] offset:192
	s_add_u32 s100, s100, 0x150000
	s_addc_u32 s101, s101, 0
	global_load_dwordx4 v[148:151], v250, s[100:101]
	global_load_dwordx4 v[152:155], v250, s[100:101] offset:64
	global_load_dwordx4 v[156:159], v250, s[100:101] offset:128
	global_load_dwordx4 v[160:163], v250, s[100:101] offset:192
	s_add_u32 s100, s100, 0x70000
	s_addc_u32 s101, s101, 0
	s_waitcnt vmcnt(12)
	v_mfma_f32_16x16x32_bf16 v[38:41], v[164:167], v[130:133], 0
	v_mfma_f32_16x16x32_bf16 v[34:37], v[198:201], v[130:133], 0
	v_mfma_f32_16x16x32_bf16 v[38:41], v[168:171], v[134:137], v[38:41]
	v_mfma_f32_16x16x32_bf16 v[34:37], v[202:205], v[134:137], v[34:37]
	v_mfma_f32_16x16x32_bf16 v[38:41], v[172:175], v[138:141], v[38:41]
	v_mfma_f32_16x16x32_bf16 v[34:37], v[206:209], v[138:141], v[34:37]
	v_mfma_f32_16x16x32_bf16 v[38:41], v[176:179], v[142:145], v[38:41]
	v_mfma_f32_16x16x32_bf16 v[34:37], v[230:233], v[142:145], v[34:37]
	global_load_dwordx4 v[164:167], v250, s[100:101]
	global_load_dwordx4 v[168:171], v250, s[100:101] offset:64
	global_load_dwordx4 v[172:175], v250, s[100:101] offset:128
	global_load_dwordx4 v[176:179], v250, s[100:101] offset:192
	s_add_u32 s100, s100, 0x150000
	s_addc_u32 s101, s101, 0
	global_load_dwordx4 v[198:201], v250, s[100:101]
	global_load_dwordx4 v[202:205], v250, s[100:101] offset:64
	global_load_dwordx4 v[206:209], v250, s[100:101] offset:128
	global_load_dwordx4 v[230:233], v250, s[100:101] offset:192
	s_add_u32 s100, s100, 0x70000
	s_addc_u32 s101, s101, 0
	s_waitcnt vmcnt(12)
; __device__ __forceinline__ f32x4 mfma16(bf16x8 a, bf16x8 b, f32x4 c) { return __builtin_amdgcn_mfma_f32_16x16x32_bf16(a, b, c, 0, 0, 0); }
; __device__ __forceinline__ void attn_phase(const bf16* proj, bf16* mixed, const float* rpb, const float* gain_a, LAS unsigned char* lds, int vb, int nb, int wave, int lane_in) {
;     ...
;         for (int tq = 0; tq < 2; ++tq) {
;             bf16x8 kf[8][4];
; #pragma unroll
;             for (int tt = 0; tt < 8; ++tt) { const int t = 8 * tq + tt;
;                 const int ktok = base + 64 * (row_start + (t >> 1)) + blk_start + 16 * (t & 1) + qi;
;                 const bf16* kp = proj + (size_t)ktok * NIN + C_AK + h * 128 + g * 8;
; #pragma unroll
;                 for (int ks = 0; ks < 4; ++ks) kf[tt][ks] = *(const bf16x8*)(kp + ks * 32); }
; #pragma unroll
;             for (int tt = 0; tt < 8; ++tt) { f32x4 a = {0.f, 0.f, 0.f, 0.f};
; #pragma unroll
;                 for (int ks = 0; ks < 4; ++ks) a = mfma16(kf[tt][ks], qf[ks], a);
;                 sc[8 * tq + tt] = a; }
;         }
;         const int qc = 16 * cb + qi, wst = min(max(qc - 8, 0), 48);
;         float mx = -3.0e38f;
; #pragma unroll
;         for (int t = 0; t < 16; ++t) {
;             const int dr = row_start + (t >> 1) - r + 7;
; #pragma unroll
;             for (int e = 0; e < 4; ++e) {
;                 const int kc = blk_start + 16 * (t & 1) + 4 * g + e, dc = min(max(kc - qc + 15, 0), 30);
;                 const bool valid = (kc >= wst) && (kc < wst + 16);
;                 const float v = valid ? sc[t][e] * 0.08838834764831845f + bt[dr * 31 + dc] : -1e30f;
;                 sc[t][e] = v; mx = fmaxf(mx, v);
	v_mfma_f32_16x16x32_bf16 v[30:33], v[234:237], v[130:133], 0
	v_mfma_f32_16x16x32_bf16 v[26:29], v[100:103], v[130:133], 0
	v_mfma_f32_16x16x32_bf16 v[30:33], v[238:241], v[134:137], v[30:33]
	v_mfma_f32_16x16x32_bf16 v[26:29], v[104:107], v[134:137], v[26:29]
	v_mfma_f32_16x16x32_bf16 v[30:33], v[242:245], v[138:141], v[30:33]
	v_mfma_f32_16x16x32_bf16 v[26:29], v[110:113], v[138:141], v[26:29]
	v_mfma_f32_16x16x32_bf16 v[30:33], v[246:249], v[142:145], v[30:33]
	v_mfma_f32_16x16x32_bf16 v[26:29], v[114:117], v[142:145], v[26:29]
	global_load_dwordx4 v[234:237], v250, s[100:101]
	global_load_dwordx4 v[238:241], v250, s[100:101] offset:64
	global_load_dwordx4 v[242:245], v250, s[100:101] offset:128
	global_load_dwordx4 v[246:249], v250, s[100:101] offset:192
	s_add_u32 s100, s100, 0x150000
	s_addc_u32 s101, s101, 0
	global_load_dwordx4 v[100:103], v250, s[100:101]
	global_load_dwordx4 v[104:107], v250, s[100:101] offset:64
	global_load_dwordx4 v[110:113], v250, s[100:101] offset:128
	global_load_dwordx4 v[114:117], v250, s[100:101] offset:192
	s_add_u32 s100, s100, 0x70000
	s_addc_u32 s101, s101, 0
	s_waitcnt vmcnt(12)
	v_mfma_f32_16x16x32_bf16 v[22:25], v[148:151], v[130:133], 0
	v_mfma_f32_16x16x32_bf16 v[18:21], v[164:167], v[130:133], 0
	v_mfma_f32_16x16x32_bf16 v[22:25], v[152:155], v[134:137], v[22:25]
	v_mfma_f32_16x16x32_bf16 v[18:21], v[168:171], v[134:137], v[18:21]
	v_mfma_f32_16x16x32_bf16 v[22:25], v[156:159], v[138:141], v[22:25]
	v_mfma_f32_16x16x32_bf16 v[18:21], v[172:175], v[138:141], v[18:21]
	v_mfma_f32_16x16x32_bf16 v[22:25], v[160:163], v[142:145], v[22:25]
	v_mfma_f32_16x16x32_bf16 v[18:21], v[176:179], v[142:145], v[18:21]
	global_load_dwordx4 v[148:151], v250, s[100:101]
	global_load_dwordx4 v[152:155], v250, s[100:101] offset:64
	global_load_dwordx4 v[156:159], v250, s[100:101] offset:128
	global_load_dwordx4 v[160:163], v250, s[100:101] offset:192
	s_waitcnt vmcnt(8)
	v_mfma_f32_16x16x32_bf16 v[14:17], v[198:201], v[130:133], 0
	v_mfma_f32_16x16x32_bf16 v[10:13], v[234:237], v[130:133], 0
	v_mfma_f32_16x16x32_bf16 v[14:17], v[202:205], v[134:137], v[14:17]
	v_mfma_f32_16x16x32_bf16 v[10:13], v[238:241], v[134:137], v[10:13]
	v_mfma_f32_16x16x32_bf16 v[14:17], v[206:209], v[138:141], v[14:17]
	v_mfma_f32_16x16x32_bf16 v[10:13], v[242:245], v[138:141], v[10:13]
	v_mfma_f32_16x16x32_bf16 v[14:17], v[230:233], v[142:145], v[14:17]
	v_mfma_f32_16x16x32_bf16 v[10:13], v[246:249], v[142:145], v[10:13]
	s_waitcnt vmcnt(0)
	v_mfma_f32_16x16x32_bf16 v[6:9], v[100:103], v[130:133], 0
	v_mfma_f32_16x16x32_bf16 v[2:5], v[148:151], v[130:133], 0
	v_mfma_f32_16x16x32_bf16 v[6:9], v[104:107], v[134:137], v[6:9]
	v_mfma_f32_16x16x32_bf16 v[2:5], v[152:155], v[134:137], v[2:5]
	v_mfma_f32_16x16x32_bf16 v[6:9], v[110:113], v[138:141], v[6:9]
	v_mfma_f32_16x16x32_bf16 v[2:5], v[156:159], v[138:141], v[2:5]
	v_mfma_f32_16x16x32_bf16 v[6:9], v[114:117], v[142:145], v[6:9]
	v_mfma_f32_16x16x32_bf16 v[2:5], v[160:163], v[142:145], v[2:5]
	s_nop 7
	s_nop 7
	s_movk_i32 s4, 0x7c
	v_mul_lo_u32 v73, v73, s4
	v_cmp_ge_i32_e32 vcc, v81, v80
	v_cmp_lt_i32_e64 s[4:5], v81, v82
	v_sub_u32_e32 v63, v81, v79
	v_add_u32_e32 v73, s62, v73
	s_nop 3
	s_and_b64 s[54:55], vcc, s[4:5]
	v_mov_b32_e32 v62, 0xf149f2ca
	v_max_i32_e32 v74, -15, v63
	v_mov_b32_e32 v63, 0xf149f2ca
	s_and_saveexec_b64 s[4:5], s[54:55]
	s_cbranch_execz .LBB0_433
	v_add_u32_e32 v63, 15, v74
	v_min_u32_e32 v63, 30, v63
	v_lshl_add_u32 v63, v63, 2, v73
	ds_read_b32 v63, v63 offset:868
	s_waitcnt lgkmcnt(0)
	v_fmac_f32_e32 v63, 0x3db504f3, v66

; #define LAS __attribute__((address_space(3)))
; #define LDS_WAIT() asm volatile("s_waitcnt lgkmcnt(0)" ::: "memory")
; __device__ __forceinline__ void transpose_item_q(const float* W, int K, int N, signed char* WT, int k0, int n0, int drow0, float sw, LAS float* scr, int lane) {
; #pragma unroll 16
;     for (int i = 0; i < 32; ++i) { const int kk = 2 * i + (lane >> 5); scr[kk * 33 + (lane & 31)] = __builtin_nontemporal_load(W + (size_t)(k0 + kk) * N + n0 + (lane & 31)); }
;     LDS_WAIT();
.LBB0_1287:
	v_add_u32_e32 v182, s5, v4
	v_lshl_add_u64 v[6:7], v[182:183], 2, v[2:3]
	global_load_dword v226, v[6:7], off nt
	v_add_u32_e32 v6, 0x2000, v182
	v_mov_b32_e32 v7, v183
	v_lshl_add_u64 v[6:7], v[6:7], 2, v[2:3]
	global_load_dword v227, v[6:7], off nt
	v_mov_b32_e32 v7, v183
	s_add_i32 s5, s5, 0x20000
	s_cmp_lg_u32 s5, 0x40000
	v_add_u32_e32 v6, 0x4000, v182
	v_lshl_add_u64 v[6:7], v[6:7], 2, v[2:3]
	global_load_dword v228, v[6:7], off nt
	v_add_u32_e32 v6, 0x6000, v182
	v_mov_b32_e32 v7, v183
	v_lshl_add_u64 v[6:7], v[6:7], 2, v[2:3]
	global_load_dword v229, v[6:7], off nt
	v_mov_b32_e32 v7, v183
	v_add_u32_e32 v6, 0x8000, v182
	v_lshl_add_u64 v[6:7], v[6:7], 2, v[2:3]
	global_load_dword v230, v[6:7], off nt
	v_add_u32_e32 v6, 0xa000, v182
	v_mov_b32_e32 v7, v183
	v_lshl_add_u64 v[6:7], v[6:7], 2, v[2:3]
	global_load_dword v231, v[6:7], off nt
	v_mov_b32_e32 v7, v183
	v_add_u32_e32 v6, 0xc000, v182
	v_lshl_add_u64 v[6:7], v[6:7], 2, v[2:3]
	global_load_dword v232, v[6:7], off nt
	v_add_u32_e32 v6, 0xe000, v182
	v_mov_b32_e32 v7, v183
	v_lshl_add_u64 v[6:7], v[6:7], 2, v[2:3]
	global_load_dword v233, v[6:7], off nt
	v_mov_b32_e32 v7, v183
	v_add_u32_e32 v6, 0x10000, v182
	v_lshl_add_u64 v[6:7], v[6:7], 2, v[2:3]
	global_load_dword v234, v[6:7], off nt
	v_add_u32_e32 v6, 0x12000, v182
	v_mov_b32_e32 v7, v183
	v_lshl_add_u64 v[6:7], v[6:7], 2, v[2:3]
	global_load_dword v235, v[6:7], off nt
	v_mov_b32_e32 v7, v183
	v_add_u32_e32 v6, 0x14000, v182
	v_lshl_add_u64 v[6:7], v[6:7], 2, v[2:3]
	global_load_dword v236, v[6:7], off nt
	v_add_u32_e32 v6, 0x16000, v182
	v_mov_b32_e32 v7, v183
	v_lshl_add_u64 v[6:7], v[6:7], 2, v[2:3]
	global_load_dword v237, v[6:7], off nt
	v_mov_b32_e32 v7, v183
	v_add_u32_e32 v6, 0x18000, v182
	v_lshl_add_u64 v[6:7], v[6:7], 2, v[2:3]
	global_load_dword v238, v[6:7], off nt
	v_add_u32_e32 v6, 0x1a000, v182
	v_mov_b32_e32 v7, v183
	v_lshl_add_u64 v[6:7], v[6:7], 2, v[2:3]
	global_load_dword v239, v[6:7], off nt
	v_mov_b32_e32 v7, v183
	v_add_u32_e32 v6, 0x1c000, v182
	v_lshl_add_u64 v[6:7], v[6:7], 2, v[2:3]
	v_add_u32_e32 v182, 0x1e000, v182
	global_load_dword v240, v[6:7], off nt
	v_lshl_add_u64 v[6:7], v[182:183], 2, v[2:3]
	global_load_dword v241, v[6:7], off nt
	v_add_u32_e32 v9, 0x400, v5
	s_waitcnt vmcnt(14)
	ds_write2_b32 v5, v226, v227 offset1:66
	s_waitcnt vmcnt(12)
	ds_write2_b32 v5, v228, v229 offset0:132 offset1:198
	s_waitcnt vmcnt(10)
	ds_write2_b32 v9, v230, v231 offset0:8 offset1:74
	s_waitcnt vmcnt(8)
	ds_write2_b32 v9, v232, v233 offset0:140 offset1:206
	v_add_u32_e32 v9, 0x800, v5
	s_waitcnt vmcnt(6)
	ds_write2_b32 v9, v234, v235 offset0:16 offset1:82
	s_waitcnt vmcnt(4)
	ds_write2_b32 v9, v236, v237 offset0:148 offset1:214
	v_add_u32_e32 v9, 0xc00, v5
	v_add_u32_e32 v5, 0x1080, v5
	s_waitcnt vmcnt(2)
	ds_write2_b32 v9, v238, v239 offset0:24 offset1:90
	s_waitcnt vmcnt(0)
	ds_write2_b32 v9, v240, v241 offset0:156 offset1:222
	s_cbranch_scc1 .LBB0_1287
; #define LAS __attribute__((address_space(3)))
; #define LDS_WAIT() asm volatile("s_waitcnt lgkmcnt(0)" ::: "memory")
; __device__ __forceinline__ void transpose_item_q(const float* W, int K, int N, signed char* WT, int k0, int n0, int drow0, float sw, LAS float* scr, int lane) {
;     ...
;     const int n = lane >> 1, hf = lane & 1; const LAS float* s = scr + (hf * 32) * 33 + n;
;     unsigned o[8];
; #pragma unroll
;     for (int d = 0; d < 8; ++d) { unsigned w = 0;
; #pragma unroll
;         for (int b = 0; b < 4; ++b) { const float q = fminf(fmaxf(rintf(s[(4 * d + b) * 33] * sw), -127.f), 127.f); w |= ((unsigned)(int)q & 0xffu) << (8 * b); }
;         o[d] = w; }
;     v4u* dst = (v4u*)(WT + (size_t)(drow0 + n) * K + k0 + hf * 32);
;     dst[0] = (v4u){o[0], o[1], o[2], o[3]}; dst[1] = (v4u){o[4], o[5], o[6], o[7]};
;     LDS_WAIT();
	s_waitcnt lgkmcnt(0)
	ds_read2_b32 v[2:3], v69 offset1:33
	s_add_i32 s5, s44, 0xfffec400
	s_lshr_b32 s5, s5, 1
	s_and_b32 s62, s5, 0x7fffffc0
	s_mov_b32 s5, 0xc0c0500
	s_waitcnt lgkmcnt(0)
	v_mul_f32_e32 v3, v73, v3
	v_mul_f32_e32 v2, v73, v2
	v_rndne_f32_e32 v3, v3
	v_rndne_f32_e32 v2, v2
	v_med3_f32 v3, v3, s38, v224
	v_med3_f32 v2, v2, s38, v224
	v_cvt_i32_f32_e32 v3, v3
	v_cvt_i32_f32_e32 v2, v2
	v_add_u32_e32 v8, 0x400, v69
	v_add_u32_e32 v28, 0x800, v69
	v_lshlrev_b32_e32 v3, 8, v3
	v_perm_b32 v4, v3, v2, s5
	ds_read2_b32 v[2:3], v69 offset0:66 offset1:99
	v_add_u32_e32 v30, 0xc00, v69
	s_waitcnt lgkmcnt(0)
	v_mul_f32_e32 v2, v73, v2
	v_rndne_f32_e32 v2, v2
	v_mul_f32_e32 v3, v73, v3
	v_med3_f32 v2, v2, s38, v224
	v_rndne_f32_e32 v3, v3
	v_cvt_i32_f32_sdwa v2, v2 dst_sel:WORD_1 dst_unused:UNUSED_PAD src0_sel:DWORD
	v_med3_f32 v3, v3, s38, v224
	v_cvt_i32_f32_sdwa v3, v3 dst_sel:BYTE_3 dst_unused:UNUSED_PAD src0_sel:DWORD
	v_and_b32_e32 v2, 0xff0000, v2
	v_or3_b32 v2, v4, v2, v3
	ds_read2_b32 v[4:5], v69 offset0:132 offset1:165
	s_waitcnt lgkmcnt(0)
	v_mul_f32_e32 v3, v73, v4
	v_mul_f32_e32 v4, v73, v5
	v_rndne_f32_e32 v4, v4
	v_rndne_f32_e32 v3, v3
	v_med3_f32 v4, v4, s38, v224
	v_med3_f32 v3, v3, s38, v224
	v_cvt_i32_f32_e32 v4, v4
	v_cvt_i32_f32_e32 v3, v3
	v_lshlrev_b32_e32 v4, 8, v4
	v_perm_b32 v3, v4, v3, s5
	ds_read2_b32 v[4:5], v69 offset0:198 offset1:231
	s_waitcnt lgkmcnt(0)
	v_mul_f32_e32 v4, v73, v4
	v_rndne_f32_e32 v4, v4
	v_mul_f32_e32 v5, v73, v5
	v_med3_f32 v4, v4, s38, v224
	v_rndne_f32_e32 v5, v5
	v_cvt_i32_f32_sdwa v4, v4 dst_sel:WORD_1 dst_unused:UNUSED_PAD src0_sel:DWORD
	v_med3_f32 v5, v5, s38, v224
	v_cvt_i32_f32_sdwa v5, v5 dst_sel:BYTE_3 dst_unused:UNUSED_PAD src0_sel:DWORD
	v_and_b32_e32 v4, 0xff0000, v4
	v_or3_b32 v3, v3, v4, v5
	ds_read2_b32 v[4:5], v8 offset0:8 offset1:41
	s_waitcnt lgkmcnt(0)
	v_mul_f32_e32 v5, v73, v5
	v_mul_f32_e32 v4, v73, v4
	v_rndne_f32_e32 v5, v5
	v_rndne_f32_e32 v4, v4
	v_med3_f32 v5, v5, s38, v224
	v_med3_f32 v4, v4, s38, v224
	v_cvt_i32_f32_e32 v5, v5
	v_cvt_i32_f32_e32 v4, v4
	v_lshlrev_b32_e32 v5, 8, v5
	v_perm_b32 v6, v5, v4, s5
	ds_read2_b32 v[4:5], v8 offset0:74 offset1:107
	s_waitcnt lgkmcnt(0)
	v_mul_f32_e32 v4, v73, v4
	v_rndne_f32_e32 v4, v4
	v_mul_f32_e32 v5, v73, v5
	v_med3_f32 v4, v4, s38, v224
	v_rndne_f32_e32 v5, v5
	v_cvt_i32_f32_sdwa v4, v4 dst_sel:WORD_1 dst_unused:UNUSED_PAD src0_sel:DWORD
	v_med3_f32 v5, v5, s38, v224
	v_cvt_i32_f32_sdwa v5, v5 dst_sel:BYTE_3 dst_unused:UNUSED_PAD src0_sel:DWORD
	v_and_b32_e32 v4, 0xff0000, v4
	v_or3_b32 v4, v6, v4, v5
	ds_read2_b32 v[6:7], v8 offset0:140 offset1:173
	s_waitcnt lgkmcnt(0)
	v_mul_f32_e32 v5, v73, v6
	v_mul_f32_e32 v6, v73, v7
	v_rndne_f32_e32 v6, v6
	v_rndne_f32_e32 v5, v5
	v_med3_f32 v6, v6, s38, v224
	v_med3_f32 v5, v5, s38, v224
	v_cvt_i32_f32_e32 v6, v6
	v_cvt_i32_f32_e32 v5, v5
	v_lshlrev_b32_e32 v6, 8, v6
	v_perm_b32 v5, v6, v5, s5
	ds_read2_b32 v[6:7], v8 offset0:206 offset1:239
	s_waitcnt lgkmcnt(0)
	v_mul_f32_e32 v6, v73, v6
	v_rndne_f32_e32 v6, v6
	v_mul_f32_e32 v7, v73, v7
	v_med3_f32 v6, v6, s38, v224
	v_rndne_f32_e32 v7, v7
	v_cvt_i32_f32_sdwa v6, v6 dst_sel:WORD_1 dst_unused:UNUSED_PAD src0_sel:DWORD
	v_med3_f32 v7, v7, s38, v224
	v_cvt_i32_f32_sdwa v7, v7 dst_sel:BYTE_3 dst_unused:UNUSED_PAD src0_sel:DWORD
	v_and_b32_e32 v6, 0xff0000, v6
	v_or3_b32 v5, v5, v6, v7
	ds_read2_b32 v[6:7], v28 offset0:16 offset1:49
	s_waitcnt lgkmcnt(0)
	v_mul_f32_e32 v7, v73, v7
	v_mul_f32_e32 v6, v73, v6
	v_rndne_f32_e32 v7, v7
	v_rndne_f32_e32 v6, v6
	v_med3_f32 v7, v7, s38, v224
	v_med3_f32 v6, v6, s38, v224
	v_cvt_i32_f32_e32 v7, v7
	v_cvt_i32_f32_e32 v6, v6
	v_lshlrev_b32_e32 v7, 8, v7
	v_perm_b32 v8, v7, v6, s5
	ds_read2_b32 v[6:7], v28 offset0:82 offset1:115
	s_waitcnt lgkmcnt(0)
	v_mul_f32_e32 v6, v73, v6
	v_rndne_f32_e32 v6, v6
	v_mul_f32_e32 v7, v73, v7
	v_med3_f32 v6, v6, s38, v224
	v_rndne_f32_e32 v7, v7
	v_cvt_i32_f32_sdwa v6, v6 dst_sel:WORD_1 dst_unused:UNUSED_PAD src0_sel:DWORD
	v_med3_f32 v7, v7, s38, v224
	v_cvt_i32_f32_sdwa v7, v7 dst_sel:BYTE_3 dst_unused:UNUSED_PAD src0_sel:DWORD
	v_and_b32_e32 v6, 0xff0000, v6
	v_or3_b32 v6, v8, v6, v7
	ds_read2_b32 v[8:9], v28 offset0:148 offset1:181
	s_waitcnt lgkmcnt(0)
	v_mul_f32_e32 v7, v73, v8
	v_mul_f32_e32 v8, v73, v9
	v_rndne_f32_e32 v8, v8
	v_rndne_f32_e32 v7, v7
	v_med3_f32 v8, v8, s38, v224
	v_med3_f32 v7, v7, s38, v224
	v_cvt_i32_f32_e32 v8, v8
	v_cvt_i32_f32_e32 v7, v7
	v_lshlrev_b32_e32 v8, 8, v8
	v_perm_b32 v7, v8, v7, s5
	ds_read2_b32 v[8:9], v28 offset0:214 offset1:247
	s_waitcnt lgkmcnt(0)
	v_mul_f32_e32 v8, v73, v8
	v_rndne_f32_e32 v8, v8
	v_mul_f32_e32 v9, v73, v9
	v_med3_f32 v8, v8, s38, v224
	v_rndne_f32_e32 v9, v9
	v_cvt_i32_f32_sdwa v8, v8 dst_sel:WORD_1 dst_unused:UNUSED_PAD src0_sel:DWORD
	v_med3_f32 v9, v9, s38, v224
	v_cvt_i32_f32_sdwa v9, v9 dst_sel:BYTE_3 dst_unused:UNUSED_PAD src0_sel:DWORD
	v_and_b32_e32 v8, 0xff0000, v8
	v_or3_b32 v7, v7, v8, v9
	ds_read2_b32 v[8:9], v30 offset0:24 offset1:57
	s_waitcnt lgkmcnt(0)
	v_mul_f32_e32 v9, v73, v9
	v_mul_f32_e32 v8, v73, v8
	v_rndne_f32_e32 v9, v9
	v_rndne_f32_e32 v8, v8
	v_med3_f32 v9, v9, s38, v224
	v_med3_f32 v8, v8, s38, v224
	v_cvt_i32_f32_e32 v9, v9
	v_cvt_i32_f32_e32 v8, v8
	v_lshlrev_b32_e32 v9, 8, v9
	v_perm_b32 v28, v9, v8, s5
	ds_read2_b32 v[8:9], v30 offset0:90 offset1:123
	s_waitcnt lgkmcnt(0)
	v_mul_f32_e32 v8, v73, v8
	v_rndne_f32_e32 v8, v8
	v_mul_f32_e32 v9, v73, v9
	v_med3_f32 v8, v8, s38, v224
	v_rndne_f32_e32 v9, v9
	v_cvt_i32_f32_sdwa v8, v8 dst_sel:WORD_1 dst_unused:UNUSED_PAD src0_sel:DWORD
	v_med3_f32 v9, v9, s38, v224
	v_cvt_i32_f32_sdwa v9, v9 dst_sel:BYTE_3 dst_unused:UNUSED_PAD src0_sel:DWORD
	v_and_b32_e32 v8, 0xff0000, v8
	v_or3_b32 v8, v28, v8, v9
	ds_read2_b32 v[28:29], v30 offset0:156 offset1:189
	s_waitcnt lgkmcnt(0)
	v_mul_f32_e32 v9, v73, v28
	v_mul_f32_e32 v28, v73, v29
	v_rndne_f32_e32 v28, v28
	v_rndne_f32_e32 v9, v9
	v_med3_f32 v28, v28, s38, v224
	v_med3_f32 v9, v9, s38, v224
	v_cvt_i32_f32_e32 v28, v28
	v_cvt_i32_f32_e32 v9, v9
	v_lshlrev_b32_e32 v28, 8, v28
	v_perm_b32 v9, v28, v9, s5
	ds_read2_b32 v[28:29], v30 offset0:222 offset1:255
	s_waitcnt lgkmcnt(0)
	v_mul_f32_e32 v28, v73, v28
	v_rndne_f32_e32 v28, v28
	v_mul_f32_e32 v29, v73, v29
	v_med3_f32 v28, v28, s38, v224
	v_rndne_f32_e32 v29, v29
	v_cvt_i32_f32_sdwa v28, v28 dst_sel:WORD_1 dst_unused:UNUSED_PAD src0_sel:DWORD
	v_med3_f32 v29, v29, s38, v224
	v_cvt_i32_f32_sdwa v29, v29 dst_sel:BYTE_3 dst_unused:UNUSED_PAD src0_sel:DWORD
	v_and_b32_e32 v28, 0xff0000, v28
	v_or3_b32 v9, v9, v28, v29
	v_or_b32_e32 v28, s4, v52
	v_mul_u32_u24_e32 v182, 0x2b00, v28
	v_lshl_add_u64 v[28:29], s[14:15], 0, v[182:183]
	v_lshl_add_u64 v[28:29], v[28:29], 0, s[62:63]
	v_lshl_add_u64 v[28:29], v[28:29], 0, v[12:13]
	global_store_dwordx4 v[28:29], v[2:5], off
	global_store_dwordx4 v[28:29], v[6:9], off offset:16
	s_waitcnt lgkmcnt(0)
	s_mov_b64 s[4:5], 0

; #define LAS __attribute__((address_space(3)))
; #define LDS_WAIT() asm volatile("s_waitcnt lgkmcnt(0)" ::: "memory")
; __device__ __forceinline__ void transpose_item_q(const float* W, int K, int N, signed char* WT, int k0, int n0, int drow0, float sw, LAS float* scr, int lane) {
; #pragma unroll 16
;     for (int i = 0; i < 32; ++i) { const int kk = 2 * i + (lane >> 5); scr[kk * 33 + (lane & 31)] = __builtin_nontemporal_load(W + (size_t)(k0 + kk) * N + n0 + (lane & 31)); }
;     LDS_WAIT();
;     const int n = lane >> 1, hf = lane & 1; const LAS float* s = scr + (hf * 32) * 33 + n;
;     unsigned o[8];
; #pragma unroll
;     for (int d = 0; d < 8; ++d) { unsigned w = 0;
; #pragma unroll
;         for (int b = 0; b < 4; ++b) { const float q = fminf(fmaxf(rintf(s[(4 * d + b) * 33] * sw), -127.f), 127.f); w |= ((unsigned)(int)q & 0xffu) << (8 * b); }
;         o[d] = w; }
;     v4u* dst = (v4u*)(WT + (size_t)(drow0 + n) * K + k0 + hf * 32);
;     dst[0] = (v4u){o[0], o[1], o[2], o[3]}; dst[1] = (v4u){o[4], o[5], o[6], o[7]};
.LBB0_1291:
	v_lshl_add_u64 v[50:51], v[46:47], 0, s[4:5]
	global_load_dword v226, v[50:51], off nt
	v_lshl_add_u64 v[50:51], v[44:45], 0, s[4:5]
	v_add_co_u32_e32 v78, vcc, 0x1582b000, v50
	s_nop 1
	v_addc_co_u32_e32 v79, vcc, 0, v51, vcc
	global_load_dword v227, v[78:79], off nt
	v_add_co_u32_e32 v78, vcc, 0x15856000, v50
	s_nop 1
	v_addc_co_u32_e32 v79, vcc, 0, v51, vcc
	v_add_co_u32_e32 v50, vcc, 0x15881000, v50
	global_load_dword v228, v[78:79], off nt
	s_nop 0
	v_addc_co_u32_e32 v51, vcc, 0, v51, vcc
	global_load_dword v229, v[50:51], off nt
	v_lshl_add_u64 v[50:51], v[42:43], 0, s[4:5]
	global_load_dword v230, v[50:51], off nt
	v_lshl_add_u64 v[50:51], v[40:41], 0, s[4:5]
	global_load_dword v231, v[50:51], off nt
	v_lshl_add_u64 v[50:51], v[38:39], 0, s[4:5]
	global_load_dword v232, v[50:51], off nt
	v_lshl_add_u64 v[50:51], v[36:37], 0, s[4:5]
	global_load_dword v233, v[50:51], off nt
	v_lshl_add_u64 v[50:51], v[34:35], 0, s[4:5]
	global_load_dword v234, v[50:51], off nt
	v_lshl_add_u64 v[50:51], v[32:33], 0, s[4:5]
	global_load_dword v235, v[50:51], off nt
	v_lshl_add_u64 v[50:51], v[30:31], 0, s[4:5]
	global_load_dword v236, v[50:51], off nt
	v_lshl_add_u64 v[50:51], v[28:29], 0, s[4:5]
	global_load_dword v237, v[50:51], off nt
	v_lshl_add_u64 v[50:51], v[8:9], 0, s[4:5]
	global_load_dword v238, v[50:51], off nt
	v_lshl_add_u64 v[50:51], v[6:7], 0, s[4:5]
	global_load_dword v239, v[50:51], off nt
	v_lshl_add_u64 v[50:51], v[4:5], 0, s[4:5]
	global_load_dword v240, v[50:51], off nt
	v_lshl_add_u64 v[50:51], v[2:3], 0, s[4:5]
	global_load_dword v241, v[50:51], off nt
	s_add_u32 s4, s4, 0x2b0000
	s_addc_u32 s5, s5, 0
	s_cmp_lg_u32 s4, 0x560000
	s_waitcnt vmcnt(14)
	ds_write2_b32 v48, v226, v227 offset1:66
	v_add_u32_e32 v242, 0x400, v48
	s_waitcnt vmcnt(12)
	ds_write2_b32 v48, v228, v229 offset0:132 offset1:198
	s_waitcnt vmcnt(10)
	ds_write2_b32 v242, v230, v231 offset0:8 offset1:74
	s_waitcnt vmcnt(8)
	ds_write2_b32 v242, v232, v233 offset0:140 offset1:206
	v_add_u32_e32 v242, 0x800, v48
	s_waitcnt vmcnt(6)
	ds_write2_b32 v242, v234, v235 offset0:16 offset1:82
	s_waitcnt vmcnt(4)
	ds_write2_b32 v242, v236, v237 offset0:148 offset1:214
	v_add_u32_e32 v242, 0xc00, v48
	v_add_u32_e32 v48, 0x1080, v48
	s_waitcnt vmcnt(2)
	ds_write2_b32 v242, v238, v239 offset0:24 offset1:90
	s_waitcnt vmcnt(0)
	ds_write2_b32 v242, v240, v241 offset0:156 offset1:222
	s_cbranch_scc1 .LBB0_1291
	s_waitcnt lgkmcnt(0)
	ds_read2_b32 v[2:3], v69 offset1:33
	s_and_b32 s28, 0xffff, s28
	s_and_b32 s4, 0xffff, s11
	s_cmpk_gt_u32 s4, 0x157
	s_cselect_b32 s5, 0xffffd500, 0
	s_waitcnt lgkmcnt(0)
	v_mul_f32_e32 v3, v72, v3
	v_mul_f32_e32 v2, v72, v2
	v_rndne_f32_e32 v3, v3
	v_rndne_f32_e32 v2, v2
	v_med3_f32 v3, v3, s38, v224
	v_med3_f32 v2, v2, s38, v224
	v_cvt_i32_f32_e32 v3, v3
	v_cvt_i32_f32_e32 v2, v2
	s_cselect_b32 s4, 0x80, 0
	s_add_i32 s5, s5, s28
	s_and_b32 s11, s28, 0x60
	v_lshlrev_b32_e32 v3, 8, v3
	s_mov_b32 s28, 0xc0c0500
	v_perm_b32 v4, v3, v2, s28
	ds_read2_b32 v[2:3], v69 offset0:66 offset1:99
	v_add_u32_e32 v8, 0x400, v69
	v_add_u32_e32 v28, 0x800, v69
	v_add_u32_e32 v30, 0xc00, v69
	s_lshl_b32 s5, s5, 1
	s_waitcnt lgkmcnt(0)
	v_mul_f32_e32 v2, v72, v2
	v_rndne_f32_e32 v2, v2
	v_mul_f32_e32 v3, v72, v3
	v_med3_f32 v2, v2, s38, v224
	v_rndne_f32_e32 v3, v3
	v_cvt_i32_f32_sdwa v2, v2 dst_sel:WORD_1 dst_unused:UNUSED_PAD src0_sel:DWORD
	v_med3_f32 v3, v3, s38, v224
	v_cvt_i32_f32_sdwa v3, v3 dst_sel:BYTE_3 dst_unused:UNUSED_PAD src0_sel:DWORD
	s_and_b32 s5, s5, 0xffffff00
	v_and_b32_e32 v2, 0xff0000, v2
	s_or_b32 s4, s4, s11
	v_or3_b32 v2, v4, v2, v3
	ds_read2_b32 v[4:5], v69 offset0:132 offset1:165
	s_or_b32 s4, s4, s5
	s_and_b32 s62, s10, 0xffff
	s_waitcnt lgkmcnt(0)
	v_mul_f32_e32 v3, v72, v4
	v_mul_f32_e32 v4, v72, v5
	v_rndne_f32_e32 v4, v4
	v_rndne_f32_e32 v3, v3
	v_med3_f32 v4, v4, s38, v224
	v_med3_f32 v3, v3, s38, v224
	v_cvt_i32_f32_e32 v4, v4
	v_cvt_i32_f32_e32 v3, v3
	v_lshlrev_b32_e32 v4, 8, v4
	v_perm_b32 v3, v4, v3, s28
	ds_read2_b32 v[4:5], v69 offset0:198 offset1:231
	s_waitcnt lgkmcnt(0)
	v_mul_f32_e32 v4, v72, v4
	v_rndne_f32_e32 v4, v4
	v_mul_f32_e32 v5, v72, v5
	v_med3_f32 v4, v4, s38, v224
	v_rndne_f32_e32 v5, v5
	v_cvt_i32_f32_sdwa v4, v4 dst_sel:WORD_1 dst_unused:UNUSED_PAD src0_sel:DWORD
	v_med3_f32 v5, v5, s38, v224
	v_cvt_i32_f32_sdwa v5, v5 dst_sel:BYTE_3 dst_unused:UNUSED_PAD src0_sel:DWORD
	v_and_b32_e32 v4, 0xff0000, v4
	v_or3_b32 v3, v3, v4, v5
	ds_read2_b32 v[4:5], v8 offset0:8 offset1:41
	s_waitcnt lgkmcnt(0)
	v_mul_f32_e32 v5, v72, v5
	v_mul_f32_e32 v4, v72, v4
	v_rndne_f32_e32 v5, v5
	v_rndne_f32_e32 v4, v4
	v_med3_f32 v5, v5, s38, v224
	v_med3_f32 v4, v4, s38, v224
	v_cvt_i32_f32_e32 v5, v5
	v_cvt_i32_f32_e32 v4, v4
	v_lshlrev_b32_e32 v5, 8, v5
	v_perm_b32 v6, v5, v4, s28
	ds_read2_b32 v[4:5], v8 offset0:74 offset1:107
	s_waitcnt lgkmcnt(0)
; #define LAS __attribute__((address_space(3)))
; #define LDS_WAIT() asm volatile("s_waitcnt lgkmcnt(0)" ::: "memory")
; __device__ __forceinline__ void transpose_item_q(const float* W, int K, int N, signed char* WT, int k0, int n0, int drow0, float sw, LAS float* scr, int lane) {
;     ...
;     const int n = lane >> 1, hf = lane & 1; const LAS float* s = scr + (hf * 32) * 33 + n;
;     unsigned o[8];
; #pragma unroll
;     for (int d = 0; d < 8; ++d) { unsigned w = 0;
; #pragma unroll
;         for (int b = 0; b < 4; ++b) { const float q = fminf(fmaxf(rintf(s[(4 * d + b) * 33] * sw), -127.f), 127.f); w |= ((unsigned)(int)q & 0xffu) << (8 * b); }
;         o[d] = w; }
;     v4u* dst = (v4u*)(WT + (size_t)(drow0 + n) * K + k0 + hf * 32);
;     dst[0] = (v4u){o[0], o[1], o[2], o[3]}; dst[1] = (v4u){o[4], o[5], o[6], o[7]};
;     LDS_WAIT();
	v_mul_f32_e32 v4, v72, v4
	v_rndne_f32_e32 v4, v4
	v_mul_f32_e32 v5, v72, v5
	v_med3_f32 v4, v4, s38, v224
	v_rndne_f32_e32 v5, v5
	v_cvt_i32_f32_sdwa v4, v4 dst_sel:WORD_1 dst_unused:UNUSED_PAD src0_sel:DWORD
	v_med3_f32 v5, v5, s38, v224
	v_cvt_i32_f32_sdwa v5, v5 dst_sel:BYTE_3 dst_unused:UNUSED_PAD src0_sel:DWORD
	v_and_b32_e32 v4, 0xff0000, v4
	v_or3_b32 v4, v6, v4, v5
	ds_read2_b32 v[6:7], v8 offset0:140 offset1:173
	s_waitcnt lgkmcnt(0)
	v_mul_f32_e32 v5, v72, v6
	v_mul_f32_e32 v6, v72, v7
	v_rndne_f32_e32 v6, v6
	v_rndne_f32_e32 v5, v5
	v_med3_f32 v6, v6, s38, v224
	v_med3_f32 v5, v5, s38, v224
	v_cvt_i32_f32_e32 v6, v6
	v_cvt_i32_f32_e32 v5, v5
	v_lshlrev_b32_e32 v6, 8, v6
	v_perm_b32 v5, v6, v5, s28
	ds_read2_b32 v[6:7], v8 offset0:206 offset1:239
	s_waitcnt lgkmcnt(0)
	v_mul_f32_e32 v6, v72, v6
	v_rndne_f32_e32 v6, v6
	v_mul_f32_e32 v7, v72, v7
	v_med3_f32 v6, v6, s38, v224
	v_rndne_f32_e32 v7, v7
	v_cvt_i32_f32_sdwa v6, v6 dst_sel:WORD_1 dst_unused:UNUSED_PAD src0_sel:DWORD
	v_med3_f32 v7, v7, s38, v224
	v_cvt_i32_f32_sdwa v7, v7 dst_sel:BYTE_3 dst_unused:UNUSED_PAD src0_sel:DWORD
	v_and_b32_e32 v6, 0xff0000, v6
	v_or3_b32 v5, v5, v6, v7
	ds_read2_b32 v[6:7], v28 offset0:16 offset1:49
	s_waitcnt lgkmcnt(0)
	v_mul_f32_e32 v7, v72, v7
	v_mul_f32_e32 v6, v72, v6
	v_rndne_f32_e32 v7, v7
	v_rndne_f32_e32 v6, v6
	v_med3_f32 v7, v7, s38, v224
	v_med3_f32 v6, v6, s38, v224
	v_cvt_i32_f32_e32 v7, v7
	v_cvt_i32_f32_e32 v6, v6
	v_lshlrev_b32_e32 v7, 8, v7
	v_perm_b32 v8, v7, v6, s28
	ds_read2_b32 v[6:7], v28 offset0:82 offset1:115
	s_waitcnt lgkmcnt(0)
	v_mul_f32_e32 v6, v72, v6
	v_rndne_f32_e32 v6, v6
	v_mul_f32_e32 v7, v72, v7
	v_med3_f32 v6, v6, s38, v224
	v_rndne_f32_e32 v7, v7
	v_cvt_i32_f32_sdwa v6, v6 dst_sel:WORD_1 dst_unused:UNUSED_PAD src0_sel:DWORD
	v_med3_f32 v7, v7, s38, v224
	v_cvt_i32_f32_sdwa v7, v7 dst_sel:BYTE_3 dst_unused:UNUSED_PAD src0_sel:DWORD
	v_and_b32_e32 v6, 0xff0000, v6
	v_or3_b32 v6, v8, v6, v7
	ds_read2_b32 v[8:9], v28 offset0:148 offset1:181
	s_waitcnt lgkmcnt(0)
	v_mul_f32_e32 v7, v72, v8
	v_mul_f32_e32 v8, v72, v9
	v_rndne_f32_e32 v8, v8
	v_rndne_f32_e32 v7, v7
	v_med3_f32 v8, v8, s38, v224
	v_med3_f32 v7, v7, s38, v224
	v_cvt_i32_f32_e32 v8, v8
	v_cvt_i32_f32_e32 v7, v7
	v_lshlrev_b32_e32 v8, 8, v8
	v_perm_b32 v7, v8, v7, s28
	ds_read2_b32 v[8:9], v28 offset0:214 offset1:247
	s_waitcnt lgkmcnt(0)
	v_mul_f32_e32 v8, v72, v8
	v_rndne_f32_e32 v8, v8
	v_mul_f32_e32 v9, v72, v9
	v_med3_f32 v8, v8, s38, v224
	v_rndne_f32_e32 v9, v9
	v_cvt_i32_f32_sdwa v8, v8 dst_sel:WORD_1 dst_unused:UNUSED_PAD src0_sel:DWORD
	v_med3_f32 v9, v9, s38, v224
	v_cvt_i32_f32_sdwa v9, v9 dst_sel:BYTE_3 dst_unused:UNUSED_PAD src0_sel:DWORD
	v_and_b32_e32 v8, 0xff0000, v8
	v_or3_b32 v7, v7, v8, v9
	ds_read2_b32 v[8:9], v30 offset0:24 offset1:57
	s_waitcnt lgkmcnt(0)
	v_mul_f32_e32 v9, v72, v9
	v_mul_f32_e32 v8, v72, v8
	v_rndne_f32_e32 v9, v9
	v_rndne_f32_e32 v8, v8
	v_med3_f32 v9, v9, s38, v224
	v_med3_f32 v8, v8, s38, v224
	v_cvt_i32_f32_e32 v9, v9
	v_cvt_i32_f32_e32 v8, v8
	v_lshlrev_b32_e32 v9, 8, v9
	v_perm_b32 v28, v9, v8, s28
	ds_read2_b32 v[8:9], v30 offset0:90 offset1:123
	s_waitcnt lgkmcnt(0)
	v_mul_f32_e32 v8, v72, v8
	v_rndne_f32_e32 v8, v8
	v_mul_f32_e32 v9, v72, v9
	v_med3_f32 v8, v8, s38, v224
	v_rndne_f32_e32 v9, v9
	v_cvt_i32_f32_sdwa v8, v8 dst_sel:WORD_1 dst_unused:UNUSED_PAD src0_sel:DWORD
	v_med3_f32 v9, v9, s38, v224
	v_cvt_i32_f32_sdwa v9, v9 dst_sel:BYTE_3 dst_unused:UNUSED_PAD src0_sel:DWORD
	v_and_b32_e32 v8, 0xff0000, v8
	v_or3_b32 v8, v28, v8, v9
	ds_read2_b32 v[28:29], v30 offset0:156 offset1:189
	s_waitcnt lgkmcnt(0)
	v_mul_f32_e32 v9, v72, v28
	v_mul_f32_e32 v28, v72, v29
	v_rndne_f32_e32 v28, v28
	v_rndne_f32_e32 v9, v9
	v_med3_f32 v28, v28, s38, v224
	v_med3_f32 v9, v9, s38, v224
	v_cvt_i32_f32_e32 v28, v28
	v_cvt_i32_f32_e32 v9, v9
	v_lshlrev_b32_e32 v28, 8, v28
	v_perm_b32 v9, v28, v9, s28
	ds_read2_b32 v[28:29], v30 offset0:222 offset1:255
	s_waitcnt lgkmcnt(0)
	v_mul_f32_e32 v28, v72, v28
	v_rndne_f32_e32 v28, v28
	v_mul_f32_e32 v29, v72, v29
	v_med3_f32 v28, v28, s38, v224
	v_rndne_f32_e32 v29, v29
	v_cvt_i32_f32_sdwa v28, v28 dst_sel:WORD_1 dst_unused:UNUSED_PAD src0_sel:DWORD
	v_med3_f32 v29, v29, s38, v224
	v_cvt_i32_f32_sdwa v29, v29 dst_sel:BYTE_3 dst_unused:UNUSED_PAD src0_sel:DWORD
	v_and_b32_e32 v28, 0xff0000, v28
	v_or3_b32 v9, v9, v28, v29
	v_or_b32_e32 v28, s4, v52
	v_ashrrev_i32_e32 v29, 31, v28
	v_lshlrev_b64 v[28:29], 12, v[28:29]
	v_lshl_add_u64 v[28:29], s[16:17], 0, v[28:29]
	v_lshl_add_u64 v[28:29], v[28:29], 0, s[62:63]
	v_lshl_add_u64 v[28:29], v[28:29], 0, v[12:13]
	global_store_dwordx4 v[28:29], v[2:5], off
	global_store_dwordx4 v[28:29], v[6:9], off offset:16
	s_waitcnt lgkmcnt(0)

; #define LAS __attribute__((address_space(3)))
; __device__ __forceinline__ unsigned pk2(float lo, float hi) { const f32x2 v = {lo, hi}; return __builtin_bit_cast(unsigned, __builtin_convertvector(v, bf16x2_t)); }
; #define LDS_WAIT() asm volatile("s_waitcnt lgkmcnt(0)" ::: "memory")
; __device__ __forceinline__ void transpose_item(const float* W, int K, int N, bf16* WT, int k0, int n0, int drow0, LAS float* scr, int lane) {
; #pragma unroll 16
;     for (int i = 0; i < 32; ++i) { const int kk = 2 * i + (lane >> 5); scr[kk * 33 + (lane & 31)] = __builtin_nontemporal_load(W + (size_t)(k0 + kk) * N + n0 + (lane & 31)); }
;     LDS_WAIT();
;     const int c = lane & 7;
; #pragma unroll
;     for (int j = 0; j < 4; ++j) { const int n = (lane >> 3) + 8 * j; const LAS float* s = scr + (8 * c) * 33 + n;
;         v4u o; o.x = pk2(s[0 * 33], s[1 * 33]); o.y = pk2(s[2 * 33], s[3 * 33]); o.z = pk2(s[4 * 33], s[5 * 33]); o.w = pk2(s[6 * 33], s[7 * 33]);
;         *(v4u*)(WT + (size_t)(drow0 + n) * K + k0 + 8 * c) = o; }
;     LDS_WAIT();
.LBB0_1296:
	v_add_u32_e32 v182, s5, v4
	v_lshl_add_u64 v[6:7], v[182:183], 2, v[2:3]
	global_load_dword v226, v[6:7], off nt
	v_add_u32_e32 v6, 0x2000, v182
	v_mov_b32_e32 v7, v183
	v_lshl_add_u64 v[6:7], v[6:7], 2, v[2:3]
	global_load_dword v227, v[6:7], off nt
	v_mov_b32_e32 v7, v183
	s_add_i32 s5, s5, 0x20000
	s_cmp_lg_u32 s5, 0x40000
	v_add_u32_e32 v6, 0x4000, v182
	v_lshl_add_u64 v[6:7], v[6:7], 2, v[2:3]
	global_load_dword v228, v[6:7], off nt
	v_add_u32_e32 v6, 0x6000, v182
	v_mov_b32_e32 v7, v183
	v_lshl_add_u64 v[6:7], v[6:7], 2, v[2:3]
	global_load_dword v229, v[6:7], off nt
	v_mov_b32_e32 v7, v183
	v_add_u32_e32 v6, 0x8000, v182
	v_lshl_add_u64 v[6:7], v[6:7], 2, v[2:3]
	global_load_dword v230, v[6:7], off nt
	v_add_u32_e32 v6, 0xa000, v182
	v_mov_b32_e32 v7, v183
	v_lshl_add_u64 v[6:7], v[6:7], 2, v[2:3]
	global_load_dword v231, v[6:7], off nt
	v_mov_b32_e32 v7, v183
	v_add_u32_e32 v6, 0xc000, v182
	v_lshl_add_u64 v[6:7], v[6:7], 2, v[2:3]
	global_load_dword v232, v[6:7], off nt
	v_add_u32_e32 v6, 0xe000, v182
	v_mov_b32_e32 v7, v183
	v_lshl_add_u64 v[6:7], v[6:7], 2, v[2:3]
	global_load_dword v233, v[6:7], off nt
	v_mov_b32_e32 v7, v183
	v_add_u32_e32 v6, 0x10000, v182
	v_lshl_add_u64 v[6:7], v[6:7], 2, v[2:3]
	global_load_dword v234, v[6:7], off nt
	v_add_u32_e32 v6, 0x12000, v182
	v_mov_b32_e32 v7, v183
	v_lshl_add_u64 v[6:7], v[6:7], 2, v[2:3]
	global_load_dword v235, v[6:7], off nt
	v_mov_b32_e32 v7, v183
	v_add_u32_e32 v6, 0x14000, v182
	v_lshl_add_u64 v[6:7], v[6:7], 2, v[2:3]
	global_load_dword v236, v[6:7], off nt
	v_add_u32_e32 v6, 0x16000, v182
	v_mov_b32_e32 v7, v183
	v_lshl_add_u64 v[6:7], v[6:7], 2, v[2:3]
	global_load_dword v237, v[6:7], off nt
	v_mov_b32_e32 v7, v183
	v_add_u32_e32 v6, 0x18000, v182
	v_lshl_add_u64 v[6:7], v[6:7], 2, v[2:3]
	global_load_dword v238, v[6:7], off nt
	v_add_u32_e32 v6, 0x1a000, v182
	v_mov_b32_e32 v7, v183
	v_lshl_add_u64 v[6:7], v[6:7], 2, v[2:3]
	global_load_dword v239, v[6:7], off nt
	v_mov_b32_e32 v7, v183
	v_add_u32_e32 v6, 0x1c000, v182
	v_lshl_add_u64 v[6:7], v[6:7], 2, v[2:3]
	v_add_u32_e32 v182, 0x1e000, v182
	global_load_dword v240, v[6:7], off nt
	v_lshl_add_u64 v[6:7], v[182:183], 2, v[2:3]
	global_load_dword v241, v[6:7], off nt
	v_add_u32_e32 v9, 0x400, v5
	s_waitcnt vmcnt(14)
	ds_write2_b32 v5, v226, v227 offset1:66
	s_waitcnt vmcnt(12)
	ds_write2_b32 v5, v228, v229 offset0:132 offset1:198
	s_waitcnt vmcnt(10)
	ds_write2_b32 v9, v230, v231 offset0:8 offset1:74
	s_waitcnt vmcnt(8)
	ds_write2_b32 v9, v232, v233 offset0:140 offset1:206
	v_add_u32_e32 v9, 0x800, v5
	s_waitcnt vmcnt(6)
	ds_write2_b32 v9, v234, v235 offset0:16 offset1:82
	s_waitcnt vmcnt(4)
	ds_write2_b32 v9, v236, v237 offset0:148 offset1:214
	v_add_u32_e32 v9, 0xc00, v5
	v_add_u32_e32 v5, 0x1080, v5
	s_waitcnt vmcnt(2)
	ds_write2_b32 v9, v238, v239 offset0:24 offset1:90
	s_waitcnt vmcnt(0)
	ds_write2_b32 v9, v240, v241 offset0:156 offset1:222
	s_cbranch_scc1 .LBB0_1296
	s_waitcnt lgkmcnt(0)
	ds_read2_b32 v[8:9], v70 offset0:33 offset1:41
	ds_read2_b32 v[28:29], v70 offset1:8
	ds_read2_b32 v[30:31], v70 offset0:66 offset1:74
	ds_read2_b32 v[32:33], v70 offset0:99 offset1:107
	ds_read2_b32 v[34:35], v70 offset0:132 offset1:140
	ds_read2_b32 v[36:37], v70 offset0:165 offset1:173
	ds_read2_b32 v[38:39], v70 offset0:198 offset1:206
	ds_read2_b32 v[40:41], v70 offset0:231 offset1:239
	s_add_i32 s5, s44, 0xffff9000
	s_and_b32 s62, s5, 0xffffff80
	s_waitcnt lgkmcnt(6)
	v_cvt_pk_bf16_f32 v2, v28, v8
	v_or_b32_e32 v8, s4, v53
	v_lshl_add_u64 v[6:7], v[14:15], 0, s[62:63]
	v_lshlrev_b32_e32 v182, 13, v8
	v_or_b32_e32 v8, s4, v1
	s_waitcnt lgkmcnt(4)
	v_cvt_pk_bf16_f32 v3, v30, v32
	s_waitcnt lgkmcnt(2)
	v_cvt_pk_bf16_f32 v4, v34, v36
	s_waitcnt lgkmcnt(0)
	v_cvt_pk_bf16_f32 v5, v38, v40
	v_lshl_add_u64 v[42:43], v[6:7], 0, v[182:183]
	v_lshlrev_b32_e32 v182, 13, v8
	global_store_dwordx4 v[42:43], v[2:5], off
	s_nop 1
	v_cvt_pk_bf16_f32 v2, v29, v9
	v_cvt_pk_bf16_f32 v3, v31, v33
	v_cvt_pk_bf16_f32 v4, v35, v37
	v_cvt_pk_bf16_f32 v5, v39, v41
	v_lshl_add_u64 v[8:9], v[6:7], 0, v[182:183]
	global_store_dwordx4 v[8:9], v[2:5], off
	ds_read2_b32 v[8:9], v70 offset0:49 offset1:57
	ds_read2_b32 v[28:29], v70 offset0:16 offset1:24
	ds_read2_b32 v[30:31], v70 offset0:82 offset1:90
	ds_read2_b32 v[32:33], v70 offset0:115 offset1:123
	ds_read2_b32 v[34:35], v70 offset0:148 offset1:156
	ds_read2_b32 v[36:37], v70 offset0:181 offset1:189
	ds_read2_b32 v[38:39], v70 offset0:214 offset1:222
	ds_read2_b32 v[40:41], v70 offset0:247 offset1:255
	s_waitcnt lgkmcnt(6)
	v_cvt_pk_bf16_f32 v2, v28, v8
	v_or_b32_e32 v8, s4, v54
	v_lshlrev_b32_e32 v182, 13, v8
	v_or_b32_e32 v8, s4, v55
	s_waitcnt lgkmcnt(4)
	v_cvt_pk_bf16_f32 v3, v30, v32
	s_waitcnt lgkmcnt(2)
	v_cvt_pk_bf16_f32 v4, v34, v36
	s_waitcnt lgkmcnt(0)
	v_cvt_pk_bf16_f32 v5, v38, v40
	v_lshl_add_u64 v[42:43], v[6:7], 0, v[182:183]
	v_lshlrev_b32_e32 v182, 13, v8
	global_store_dwordx4 v[42:43], v[2:5], off
	v_lshl_add_u64 v[6:7], v[6:7], 0, v[182:183]
	s_nop 0
	v_cvt_pk_bf16_f32 v2, v29, v9
	v_cvt_pk_bf16_f32 v3, v31, v33
	v_cvt_pk_bf16_f32 v4, v35, v37
	v_cvt_pk_bf16_f32 v5, v39, v41
	global_store_dwordx4 v[6:7], v[2:5], off
	s_waitcnt lgkmcnt(0)

; __device__ __forceinline__ unsigned pkh(float a, float b) { const f2v_t f = {a, b}; const h2v_t h = __builtin_convertvector(f, h2v_t); return __builtin_bit_cast(unsigned, h); }
; #define LAS __attribute__((address_space(3)))
; #define LDS_WAIT() asm volatile("s_waitcnt lgkmcnt(0)" ::: "memory")
; __device__ __forceinline__ void transpose_item_h(const float* W, int K, int N, bf16* WT, int k0, int n0, int drow0, LAS float* scr, int lane) {
; #pragma unroll 16
;     for (int i = 0; i < 32; ++i) { const int kk = 2 * i + (lane >> 5); scr[kk * 33 + (lane & 31)] = __builtin_nontemporal_load(W + (size_t)(k0 + kk) * N + n0 + (lane & 31)); }
;     LDS_WAIT();
;     const int c = lane & 7;
; #pragma unroll
;     for (int j = 0; j < 4; ++j) { const int n = (lane >> 3) + 8 * j; const LAS float* s = scr + (8 * c) * 33 + n;
;         v4u o; o.x = pg8::pkh(s[0 * 33], s[1 * 33]); o.y = pg8::pkh(s[2 * 33], s[3 * 33]); o.z = pg8::pkh(s[4 * 33], s[5 * 33]); o.w = pg8::pkh(s[6 * 33], s[7 * 33]);
;         *(v4u*)(WT + (size_t)(drow0 + n) * K + k0 + 8 * c) = o; }
;     LDS_WAIT();
.LBB0_1302:
	v_lshl_add_u64 v[96:97], v[50:51], 0, s[36:37]
	global_load_dword v226, v[96:97], off nt
	v_lshl_add_u64 v[96:97], v[48:49], 0, s[36:37]
	global_load_dword v227, v[96:97], off nt
	v_lshl_add_u64 v[96:97], v[46:47], 0, s[36:37]
	global_load_dword v228, v[96:97], off nt
	v_lshl_add_u64 v[96:97], v[44:45], 0, s[36:37]
	global_load_dword v229, v[96:97], off nt
	v_lshl_add_u64 v[96:97], v[42:43], 0, s[36:37]
	global_load_dword v230, v[96:97], off nt
	v_lshl_add_u64 v[96:97], v[40:41], 0, s[36:37]
	global_load_dword v231, v[96:97], off nt
	v_lshl_add_u64 v[96:97], v[38:39], 0, s[36:37]
	global_load_dword v232, v[96:97], off nt
	v_lshl_add_u64 v[96:97], v[36:37], 0, s[36:37]
	global_load_dword v233, v[96:97], off nt
	v_lshl_add_u64 v[96:97], v[34:35], 0, s[36:37]
	global_load_dword v234, v[96:97], off nt
	v_lshl_add_u64 v[96:97], v[32:33], 0, s[36:37]
	global_load_dword v235, v[96:97], off nt
	v_lshl_add_u64 v[96:97], v[30:31], 0, s[36:37]
	global_load_dword v236, v[96:97], off nt
	v_lshl_add_u64 v[96:97], v[28:29], 0, s[36:37]
	global_load_dword v237, v[96:97], off nt
	v_lshl_add_u64 v[96:97], v[8:9], 0, s[36:37]
	global_load_dword v238, v[96:97], off nt
	v_lshl_add_u64 v[96:97], v[6:7], 0, s[36:37]
	global_load_dword v239, v[96:97], off nt
	v_lshl_add_u64 v[96:97], v[4:5], 0, s[36:37]
	global_load_dword v240, v[96:97], off nt
	v_lshl_add_u64 v[96:97], v[2:3], 0, s[36:37]
	global_load_dword v241, v[96:97], off nt
	s_add_u32 s36, s36, 0x1c0000
	s_addc_u32 s37, s37, 0
	s_cmp_lg_u32 s36, 0x380000
	v_add_u32_e32 v98, 0x400, v94
	s_waitcnt vmcnt(14)
	ds_write2_b32 v94, v226, v227 offset1:66
	s_waitcnt vmcnt(12)
	ds_write2_b32 v94, v228, v229 offset0:132 offset1:198
	s_waitcnt vmcnt(10)
	ds_write2_b32 v98, v230, v231 offset0:8 offset1:74
	s_waitcnt vmcnt(8)
	ds_write2_b32 v98, v232, v233 offset0:140 offset1:206
	v_add_u32_e32 v98, 0x800, v94
	s_waitcnt vmcnt(6)
	ds_write2_b32 v98, v234, v235 offset0:16 offset1:82
	s_waitcnt vmcnt(4)
	ds_write2_b32 v98, v236, v237 offset0:148 offset1:214
	v_add_u32_e32 v98, 0xc00, v94
	v_add_u32_e32 v94, 0x1080, v94
	s_waitcnt vmcnt(2)
	ds_write2_b32 v98, v238, v239 offset0:24 offset1:90
	s_waitcnt vmcnt(0)
	ds_write2_b32 v98, v240, v241 offset0:156 offset1:222
	s_cbranch_scc1 .LBB0_1302
	s_waitcnt lgkmcnt(0)
	ds_read2_b32 v[8:9], v70 offset0:33 offset1:41
	ds_read2_b32 v[28:29], v70 offset1:8
	ds_read2_b32 v[30:31], v70 offset0:66 offset1:74
	ds_read2_b32 v[32:33], v70 offset0:99 offset1:107
	ds_read2_b32 v[34:35], v70 offset0:132 offset1:140
	ds_read2_b32 v[36:37], v70 offset0:165 offset1:173
	ds_read2_b32 v[38:39], v70 offset0:198 offset1:206
	ds_read2_b32 v[40:41], v70 offset0:231 offset1:239
	s_add_i32 s5, s30, s28
	s_add_i32 s31, s5, 0xfffff000
	s_ashr_i32 s5, s4, 31
	s_waitcnt lgkmcnt(6)
	v_cvt_pk_f16_f32 v2, v28, v8
	v_or_b32_e32 v8, s31, v53
	v_lshl_add_u64 v[6:7], s[4:5], 1, v[16:17]
	v_lshlrev_b32_e32 v182, 13, v8
	v_or_b32_e32 v8, s31, v1
	s_waitcnt lgkmcnt(4)
	v_cvt_pk_f16_f32 v3, v30, v32
	s_waitcnt lgkmcnt(2)
	v_cvt_pk_f16_f32 v4, v34, v36
	s_waitcnt lgkmcnt(0)
	v_cvt_pk_f16_f32 v5, v38, v40
	v_lshl_add_u64 v[42:43], v[6:7], 0, v[182:183]
	v_lshlrev_b32_e32 v182, 13, v8
	global_store_dwordx4 v[42:43], v[2:5], off
	s_mov_b64 s[36:37], 0
	s_nop 0
	v_cvt_pk_f16_f32 v2, v29, v9
	v_cvt_pk_f16_f32 v3, v31, v33
	v_cvt_pk_f16_f32 v4, v35, v37
	v_cvt_pk_f16_f32 v5, v39, v41
	v_lshl_add_u64 v[8:9], v[6:7], 0, v[182:183]
	global_store_dwordx4 v[8:9], v[2:5], off
	ds_read2_b32 v[8:9], v70 offset0:49 offset1:57
	ds_read2_b32 v[28:29], v70 offset0:16 offset1:24
	ds_read2_b32 v[30:31], v70 offset0:82 offset1:90
	ds_read2_b32 v[32:33], v70 offset0:115 offset1:123
	ds_read2_b32 v[34:35], v70 offset0:148 offset1:156
	ds_read2_b32 v[36:37], v70 offset0:181 offset1:189
	ds_read2_b32 v[38:39], v70 offset0:214 offset1:222
	ds_read2_b32 v[40:41], v70 offset0:247 offset1:255
	s_waitcnt lgkmcnt(6)
	v_cvt_pk_f16_f32 v2, v28, v8
	v_or_b32_e32 v8, s31, v54
	v_lshlrev_b32_e32 v182, 13, v8
	v_or_b32_e32 v8, s31, v55
	s_waitcnt lgkmcnt(4)
	v_cvt_pk_f16_f32 v3, v30, v32
	s_waitcnt lgkmcnt(2)
	v_cvt_pk_f16_f32 v4, v34, v36
	s_waitcnt lgkmcnt(0)
	v_cvt_pk_f16_f32 v5, v38, v40
	v_lshl_add_u64 v[42:43], v[6:7], 0, v[182:183]
	v_lshlrev_b32_e32 v182, 13, v8
	global_store_dwordx4 v[42:43], v[2:5], off
	v_lshl_add_u64 v[6:7], v[6:7], 0, v[182:183]
	s_nop 0
	v_cvt_pk_f16_f32 v2, v29, v9
	v_cvt_pk_f16_f32 v3, v31, v33
	v_cvt_pk_f16_f32 v4, v35, v37
	v_cvt_pk_f16_f32 v5, v39, v41
	global_store_dwordx4 v[6:7], v[2:5], off
	s_waitcnt lgkmcnt(0)

; #define LAS __attribute__((address_space(3)))
; #define LDS_WAIT() asm volatile("s_waitcnt lgkmcnt(0)" ::: "memory")
; __device__ __forceinline__ void transpose_item_qc(const float* W, int K, int N, signed char* WT, int k0, int n0, int drow0, const unsigned* colmax_bits, LAS float* scr, int lane) {
; #pragma unroll 16
;     for (int i = 0; i < 32; ++i) { const int kk = 2 * i + (lane >> 5); scr[kk * 33 + (lane & 31)] = __builtin_nontemporal_load(W + (size_t)(k0 + kk) * N + n0 + (lane & 31)); }
;     LDS_WAIT();
;     const int n = lane >> 1, hf = lane & 1; const LAS float* s = scr + (hf * 32) * 33 + n;
;     const float sw = 127.0f / fmaxf(__builtin_bit_cast(float, colmax_bits[n0 + n]), 1e-30f);
;     unsigned o[8];
; #pragma unroll
;     for (int dd = 0; dd < 8; ++dd) { unsigned w = 0;
; #pragma unroll
;         for (int b = 0; b < 4; ++b) { const float q = fminf(fmaxf(rintf(s[(4 * dd + b) * 33] * sw), -127.f), 127.f); w |= ((unsigned)(int)q & 0xffu) << (8 * b); }
;         o[dd] = w; }
;     v4u* dst = (v4u*)(WT + (size_t)(drow0 + n) * K + k0 + hf * 32);
;     dst[0] = (v4u){o[0], o[1], o[2], o[3]}; dst[1] = (v4u){o[4], o[5], o[6], o[7]};
;     LDS_WAIT();
.LBB0_1306:
	v_lshl_add_u64 v[80:81], v[50:51], 0, s[36:37]
	global_load_dword v226, v[80:81], off nt
	v_lshl_add_u64 v[80:81], v[48:49], 0, s[36:37]
	global_load_dword v227, v[80:81], off nt
	v_lshl_add_u64 v[80:81], v[46:47], 0, s[36:37]
	global_load_dword v228, v[80:81], off nt
	v_lshl_add_u64 v[80:81], v[44:45], 0, s[36:37]
	global_load_dword v229, v[80:81], off nt
	v_lshl_add_u64 v[80:81], v[42:43], 0, s[36:37]
	global_load_dword v230, v[80:81], off nt
	v_lshl_add_u64 v[80:81], v[40:41], 0, s[36:37]
	global_load_dword v231, v[80:81], off nt
	v_lshl_add_u64 v[80:81], v[38:39], 0, s[36:37]
	global_load_dword v232, v[80:81], off nt
	v_lshl_add_u64 v[80:81], v[36:37], 0, s[36:37]
	global_load_dword v233, v[80:81], off nt
	v_lshl_add_u64 v[80:81], v[34:35], 0, s[36:37]
	global_load_dword v234, v[80:81], off nt
	v_lshl_add_u64 v[80:81], v[32:33], 0, s[36:37]
	global_load_dword v235, v[80:81], off nt
	v_lshl_add_u64 v[80:81], v[30:31], 0, s[36:37]
	global_load_dword v236, v[80:81], off nt
	v_lshl_add_u64 v[80:81], v[28:29], 0, s[36:37]
	global_load_dword v237, v[80:81], off nt
	v_lshl_add_u64 v[80:81], v[8:9], 0, s[36:37]
	global_load_dword v238, v[80:81], off nt
	v_lshl_add_u64 v[80:81], v[6:7], 0, s[36:37]
	global_load_dword v239, v[80:81], off nt
	v_lshl_add_u64 v[80:81], v[4:5], 0, s[36:37]
	global_load_dword v240, v[80:81], off nt
	v_lshl_add_u64 v[80:81], v[2:3], 0, s[36:37]
	global_load_dword v241, v[80:81], off nt
	s_add_u32 s36, s36, 0x1c0000
	s_addc_u32 s37, s37, 0
	s_cmp_lg_u32 s36, 0x380000
	v_add_u32_e32 v82, 0x400, v78
	s_waitcnt vmcnt(14)
	ds_write2_b32 v78, v226, v227 offset1:66
	s_waitcnt vmcnt(12)
	ds_write2_b32 v78, v228, v229 offset0:132 offset1:198
	s_waitcnt vmcnt(10)
	ds_write2_b32 v82, v230, v231 offset0:8 offset1:74
	s_waitcnt vmcnt(8)
	ds_write2_b32 v82, v232, v233 offset0:140 offset1:206
	v_add_u32_e32 v82, 0x800, v78
	s_waitcnt vmcnt(6)
	ds_write2_b32 v82, v234, v235 offset0:16 offset1:82
	s_waitcnt vmcnt(4)
	ds_write2_b32 v82, v236, v237 offset0:148 offset1:214
	v_add_u32_e32 v82, 0xc00, v78
	v_add_u32_e32 v78, 0x1080, v78
	s_waitcnt vmcnt(2)
	ds_write2_b32 v82, v238, v239 offset0:24 offset1:90
	s_waitcnt vmcnt(0)
	ds_write2_b32 v82, v240, v241 offset0:156 offset1:222
	s_cbranch_scc1 .LBB0_1306
	v_or_b32_e32 v2, s10, v52
	v_ashrrev_i32_e32 v3, 31, v2
	s_waitcnt lgkmcnt(0)
	v_lshl_add_u64 v[2:3], v[2:3], 2, s[8:9]
	global_load_dword v2, v[2:3], off
	v_add_u32_e32 v8, 0x400, v69
	v_add_u32_e32 v30, 0xc00, v69
	s_add_i32 s5, s30, 0xfffff800
	s_cmp_lt_i32 s29, 16
	s_cselect_b32 s5, s30, s5
	s_waitcnt vmcnt(0)
	v_max_f32_e32 v2, v2, v2
	v_max_f32_e32 v2, 0xda24260, v2
	v_div_scale_f32 v3, s[10:11], v2, v2, s41
	v_rcp_f32_e32 v4, v3
	s_mov_b32 s10, 0xc0c0500
	v_fma_f32 v5, -v3, v4, 1.0
	v_fmac_f32_e32 v4, v5, v4
	v_div_scale_f32 v5, vcc, s41, v2, s41
	v_mul_f32_e32 v6, v5, v4
	v_fma_f32 v7, -v3, v6, v5
	v_fmac_f32_e32 v6, v7, v4
	v_fma_f32 v3, -v3, v6, v5
	v_div_fmas_f32 v3, v3, v4, v6
	v_div_fixup_f32 v9, v3, v2, s41
	ds_read2_b32 v[2:3], v69 offset1:33
	s_waitcnt lgkmcnt(0)
	v_mul_f32_e32 v3, v9, v3
	v_mul_f32_e32 v2, v2, v9
	v_rndne_f32_e32 v3, v3
	v_rndne_f32_e32 v2, v2
	v_med3_f32 v3, v3, s38, v224
	v_med3_f32 v2, v2, s38, v224
	v_cvt_i32_f32_e32 v3, v3
	v_cvt_i32_f32_e32 v2, v2
	v_lshlrev_b32_e32 v3, 8, v3
	v_perm_b32 v4, v3, v2, s10
	ds_read2_b32 v[2:3], v69 offset0:66 offset1:99
	s_waitcnt lgkmcnt(0)
	v_mul_f32_e32 v2, v9, v2
	v_rndne_f32_e32 v2, v2
	v_mul_f32_e32 v3, v9, v3
	v_med3_f32 v2, v2, s38, v224
	v_rndne_f32_e32 v3, v3
	v_cvt_i32_f32_sdwa v2, v2 dst_sel:WORD_1 dst_unused:UNUSED_PAD src0_sel:DWORD
	v_med3_f32 v3, v3, s38, v224
	v_cvt_i32_f32_sdwa v3, v3 dst_sel:BYTE_3 dst_unused:UNUSED_PAD src0_sel:DWORD
	v_and_b32_e32 v2, 0xff0000, v2
	v_or3_b32 v2, v4, v2, v3
	ds_read2_b32 v[4:5], v69 offset0:132 offset1:165
	s_waitcnt lgkmcnt(0)
	v_mul_f32_e32 v3, v9, v4
	v_mul_f32_e32 v4, v9, v5
	v_rndne_f32_e32 v4, v4
	v_rndne_f32_e32 v3, v3
	v_med3_f32 v4, v4, s38, v224
	v_med3_f32 v3, v3, s38, v224
	v_cvt_i32_f32_e32 v4, v4
	v_cvt_i32_f32_e32 v3, v3
	v_lshlrev_b32_e32 v4, 8, v4
	v_perm_b32 v3, v4, v3, s10
	ds_read2_b32 v[4:5], v69 offset0:198 offset1:231
	s_waitcnt lgkmcnt(0)
	v_mul_f32_e32 v4, v9, v4
	v_rndne_f32_e32 v4, v4
	v_mul_f32_e32 v5, v9, v5
	v_med3_f32 v4, v4, s38, v224
	v_rndne_f32_e32 v5, v5
	v_cvt_i32_f32_sdwa v4, v4 dst_sel:WORD_1 dst_unused:UNUSED_PAD src0_sel:DWORD
	v_med3_f32 v5, v5, s38, v224
	v_cvt_i32_f32_sdwa v5, v5 dst_sel:BYTE_3 dst_unused:UNUSED_PAD src0_sel:DWORD
	v_and_b32_e32 v4, 0xff0000, v4
	v_or3_b32 v3, v3, v4, v5
	ds_read2_b32 v[4:5], v8 offset0:8 offset1:41
	s_waitcnt lgkmcnt(0)
	v_mul_f32_e32 v5, v9, v5
	v_mul_f32_e32 v4, v9, v4
	v_rndne_f32_e32 v5, v5
	v_rndne_f32_e32 v4, v4
	v_med3_f32 v5, v5, s38, v224
	v_med3_f32 v4, v4, s38, v224
	v_cvt_i32_f32_e32 v5, v5
	v_cvt_i32_f32_e32 v4, v4
	v_lshlrev_b32_e32 v5, 8, v5
	v_perm_b32 v6, v5, v4, s10
	ds_read2_b32 v[4:5], v8 offset0:74 offset1:107
	s_waitcnt lgkmcnt(0)
; #define LDS_WAIT() asm volatile("s_waitcnt lgkmcnt(0)" ::: "memory")
; __device__ __forceinline__ void transpose_item_qc(const float* W, int K, int N, signed char* WT, int k0, int n0, int drow0, const unsigned* colmax_bits, LAS float* scr, int lane) {
;     ...
;     for (int dd = 0; dd < 8; ++dd) { unsigned w = 0;
; #pragma unroll
;         for (int b = 0; b < 4; ++b) { const float q = fminf(fmaxf(rintf(s[(4 * dd + b) * 33] * sw), -127.f), 127.f); w |= ((unsigned)(int)q & 0xffu) << (8 * b); }
;         o[dd] = w; }
;     v4u* dst = (v4u*)(WT + (size_t)(drow0 + n) * K + k0 + hf * 32);
;     dst[0] = (v4u){o[0], o[1], o[2], o[3]}; dst[1] = (v4u){o[4], o[5], o[6], o[7]};
;     LDS_WAIT();
	v_mul_f32_e32 v4, v9, v4
	v_rndne_f32_e32 v4, v4
	v_mul_f32_e32 v5, v9, v5
	v_med3_f32 v4, v4, s38, v224
	v_rndne_f32_e32 v5, v5
	v_cvt_i32_f32_sdwa v4, v4 dst_sel:WORD_1 dst_unused:UNUSED_PAD src0_sel:DWORD
	v_med3_f32 v5, v5, s38, v224
	v_cvt_i32_f32_sdwa v5, v5 dst_sel:BYTE_3 dst_unused:UNUSED_PAD src0_sel:DWORD
	v_and_b32_e32 v4, 0xff0000, v4
	v_or3_b32 v4, v6, v4, v5
	ds_read2_b32 v[6:7], v8 offset0:140 offset1:173
	s_waitcnt lgkmcnt(0)
	v_mul_f32_e32 v5, v9, v6
	v_mul_f32_e32 v6, v9, v7
	v_rndne_f32_e32 v6, v6
	v_rndne_f32_e32 v5, v5
	v_med3_f32 v6, v6, s38, v224
	v_med3_f32 v5, v5, s38, v224
	v_cvt_i32_f32_e32 v6, v6
	v_cvt_i32_f32_e32 v5, v5
	v_lshlrev_b32_e32 v6, 8, v6
	v_perm_b32 v5, v6, v5, s10
	ds_read2_b32 v[6:7], v8 offset0:206 offset1:239
	v_add_u32_e32 v8, 0x800, v69
	s_waitcnt lgkmcnt(0)
	v_mul_f32_e32 v6, v9, v6
	v_rndne_f32_e32 v6, v6
	v_mul_f32_e32 v7, v9, v7
	v_med3_f32 v6, v6, s38, v224
	v_rndne_f32_e32 v7, v7
	v_cvt_i32_f32_sdwa v6, v6 dst_sel:WORD_1 dst_unused:UNUSED_PAD src0_sel:DWORD
	v_med3_f32 v7, v7, s38, v224
	v_cvt_i32_f32_sdwa v7, v7 dst_sel:BYTE_3 dst_unused:UNUSED_PAD src0_sel:DWORD
	v_and_b32_e32 v6, 0xff0000, v6
	v_or3_b32 v5, v5, v6, v7
	ds_read2_b32 v[6:7], v8 offset0:16 offset1:49
	s_waitcnt lgkmcnt(0)
	v_mul_f32_e32 v7, v9, v7
	v_mul_f32_e32 v6, v9, v6
	v_rndne_f32_e32 v7, v7
	v_rndne_f32_e32 v6, v6
	v_med3_f32 v7, v7, s38, v224
	v_med3_f32 v6, v6, s38, v224
	v_cvt_i32_f32_e32 v7, v7
	v_cvt_i32_f32_e32 v6, v6
	v_lshlrev_b32_e32 v7, 8, v7
	v_perm_b32 v28, v7, v6, s10
	ds_read2_b32 v[6:7], v8 offset0:82 offset1:115
	s_waitcnt lgkmcnt(0)
	v_mul_f32_e32 v6, v9, v6
	v_rndne_f32_e32 v6, v6
	v_mul_f32_e32 v7, v9, v7
	v_med3_f32 v6, v6, s38, v224
	v_rndne_f32_e32 v7, v7
	v_cvt_i32_f32_sdwa v6, v6 dst_sel:WORD_1 dst_unused:UNUSED_PAD src0_sel:DWORD
	v_med3_f32 v7, v7, s38, v224
	v_cvt_i32_f32_sdwa v7, v7 dst_sel:BYTE_3 dst_unused:UNUSED_PAD src0_sel:DWORD
	v_and_b32_e32 v6, 0xff0000, v6
	v_or3_b32 v6, v28, v6, v7
	ds_read2_b32 v[28:29], v8 offset0:148 offset1:181
	s_waitcnt lgkmcnt(0)
	v_mul_f32_e32 v7, v9, v28
	v_mul_f32_e32 v28, v9, v29
	v_rndne_f32_e32 v28, v28
	v_rndne_f32_e32 v7, v7
	v_med3_f32 v28, v28, s38, v224
	v_med3_f32 v7, v7, s38, v224
	v_cvt_i32_f32_e32 v28, v28
	v_cvt_i32_f32_e32 v7, v7
	v_lshlrev_b32_e32 v28, 8, v28
	v_perm_b32 v7, v28, v7, s10
	ds_read2_b32 v[28:29], v8 offset0:214 offset1:247
	s_waitcnt lgkmcnt(0)
	v_mul_f32_e32 v8, v9, v28
	v_rndne_f32_e32 v8, v8
	v_mul_f32_e32 v28, v9, v29
	v_med3_f32 v8, v8, s38, v224
	v_rndne_f32_e32 v28, v28
	v_cvt_i32_f32_sdwa v8, v8 dst_sel:WORD_1 dst_unused:UNUSED_PAD src0_sel:DWORD
	v_med3_f32 v28, v28, s38, v224
	v_cvt_i32_f32_sdwa v28, v28 dst_sel:BYTE_3 dst_unused:UNUSED_PAD src0_sel:DWORD
	v_and_b32_e32 v8, 0xff0000, v8
	v_or3_b32 v7, v7, v8, v28
	ds_read2_b32 v[28:29], v30 offset0:24 offset1:57
	s_waitcnt lgkmcnt(0)
	v_mul_f32_e32 v8, v9, v28
	v_mul_f32_e32 v28, v9, v29
	v_rndne_f32_e32 v28, v28
	v_rndne_f32_e32 v8, v8
	v_med3_f32 v28, v28, s38, v224
	v_med3_f32 v8, v8, s38, v224
	v_cvt_i32_f32_e32 v28, v28
	v_cvt_i32_f32_e32 v8, v8
	v_lshlrev_b32_e32 v28, 8, v28
	v_perm_b32 v8, v28, v8, s10
	ds_read2_b32 v[28:29], v30 offset0:90 offset1:123
	s_waitcnt lgkmcnt(0)
	v_mul_f32_e32 v28, v9, v28
	v_rndne_f32_e32 v28, v28
	v_mul_f32_e32 v29, v9, v29
	v_med3_f32 v28, v28, s38, v224
	v_rndne_f32_e32 v29, v29
	v_cvt_i32_f32_sdwa v28, v28 dst_sel:WORD_1 dst_unused:UNUSED_PAD src0_sel:DWORD
	v_med3_f32 v29, v29, s38, v224
	v_cvt_i32_f32_sdwa v29, v29 dst_sel:BYTE_3 dst_unused:UNUSED_PAD src0_sel:DWORD
	v_and_b32_e32 v28, 0xff0000, v28
	v_or3_b32 v8, v8, v28, v29
	ds_read2_b32 v[28:29], v30 offset0:156 offset1:189
	s_waitcnt lgkmcnt(0)
	v_mul_f32_e32 v29, v9, v29
	v_mul_f32_e32 v28, v9, v28
	v_rndne_f32_e32 v29, v29
	v_rndne_f32_e32 v28, v28
	v_med3_f32 v29, v29, s38, v224
	v_med3_f32 v28, v28, s38, v224
	v_cvt_i32_f32_e32 v29, v29
	v_cvt_i32_f32_e32 v28, v28
	v_lshlrev_b32_e32 v29, 8, v29
	v_perm_b32 v31, v29, v28, s10
	ds_read2_b32 v[28:29], v30 offset0:222 offset1:255
	s_waitcnt lgkmcnt(0)
	v_mul_f32_e32 v28, v9, v28
	v_rndne_f32_e32 v28, v28
	v_mul_f32_e32 v9, v9, v29
	v_med3_f32 v28, v28, s38, v224
	v_rndne_f32_e32 v9, v9
	v_cvt_i32_f32_sdwa v28, v28 dst_sel:WORD_1 dst_unused:UNUSED_PAD src0_sel:DWORD
	v_med3_f32 v9, v9, s38, v224
	v_cvt_i32_f32_sdwa v9, v9 dst_sel:BYTE_3 dst_unused:UNUSED_PAD src0_sel:DWORD
	v_and_b32_e32 v28, 0xff0000, v28
	v_or3_b32 v9, v31, v28, v9
	v_or_b32_e32 v28, s5, v52
	v_or_b32_e32 v28, s28, v28
	v_ashrrev_i32_e32 v29, 31, v28
	v_lshlrev_b64 v[28:29], 12, v[28:29]
	v_lshl_add_u64 v[28:29], s[6:7], 0, v[28:29]
	s_ashr_i32 s5, s4, 31
	v_lshl_add_u64 v[28:29], v[28:29], 0, s[4:5]
	v_lshl_add_u64 v[28:29], v[28:29], 0, v[12:13]
	global_store_dwordx4 v[28:29], v[2:5], off
	global_store_dwordx4 v[28:29], v[6:9], off offset:16
	s_waitcnt lgkmcnt(0)
	s_branch .LBB0_1282
